# P4: S3 per-head parameter loads issued before the G stores; 16x16 triangular inverse with batched LDS reads and column-ordered FMAs; fast-epilogue cleanup
# speedup vs baseline: 1.0750x; 1.0067x over previous
; __device__ __forceinline__ unsigned pk2(float lo, float hi) { const f32x2 v = {lo, hi}; const bf16x2_t b = __builtin_convertvector(v, bf16x2_t); return __builtin_bit_cast(unsigned, b); }
; __device__ __forceinline__ float frcp(float x) { return __builtin_amdgcn_rcpf(x); }
;     __device__ __forceinline__ void operator()(const f32x4 (&acc)[2][2][4][2], const Unit& u, int wr, int wc, int fr, int fq) const {
;         const int row0 = u.pm * 256 + wr * 64 + fr, col0 = u.pn * 128 + wc * 32 + 8 * fq;
; #pragma unroll
;         for (int ai = 0; ai < 2; ++ai)
; #pragma unroll
;             for (int m = 0; m < 4; ++m) {
;                 const int row = row0 + ai * 128 + m * 16; const float rs = row_rstd_q(ssq, row, fq);
;                 float h[8];
; #pragma unroll
;                 for (int n = 0; n < 2; ++n) {
;                     const f32x4 a = acc[ai][0][m][n] * rs, b = acc[ai][1][m][n] * rs;
; #pragma unroll
;                     for (int j = 0; j < 4; ++j) h[4 * n + j] = a[j] * frcp(1.0f + __expf(-a[j])) * b[j];
;                 }
;                 u32x4 w; w.x = pk2(h[0], h[1]); w.y = pk2(h[2], h[3]); w.z = pk2(h[4], h[5]); w.w = pk2(h[6], h[7]);
;                 *(u32x4*)(O + (size_t)row * FF_ + col0) = w;
;             }
.Lmy_p1_fast:
	v_lshl_add_u32 v152, s8, 8, v1
	v_mov_b64_e32 v[148:149], s[26:27]
	v_lshl_or_b32 v150, s9, 7, v155
	v_ashrrev_i32_e32 v151, 31, v150
	v_lshlrev_b64 v[150:151], 1, v[150:151]
	v_or_b32_e32 v166, 16, v152
	v_mad_i64_i32 v[164:165], s[8:9], v152, s48, v[148:149]
	v_lshl_add_u64 v[164:165], v[164:165], 0, v[150:151]
	v_mov_b32_e32 v170, v232
	v_pk_mul_f32 v[126:127], v[126:127], v[170:171] op_sel_hi:[1,0]
	v_pk_mul_f32 v[128:129], v[128:129], v[170:171] op_sel_hi:[1,0]
	v_pk_mul_f32 v[122:123], v[122:123], v[170:171] op_sel_hi:[1,0]
	v_pk_mul_f32 v[124:125], v[124:125], v[170:171] op_sel_hi:[1,0]
	v_pk_mul_f32 v[118:119], v[118:119], v[170:171] op_sel_hi:[1,0]
	v_pk_mul_f32 v[120:121], v[120:121], v[170:171] op_sel_hi:[1,0]
	v_pk_mul_f32 v[114:115], v[114:115], v[170:171] op_sel_hi:[1,0]
	v_pk_mul_f32 v[116:117], v[116:117], v[170:171] op_sel_hi:[1,0]
	v_mul_f32_e32 v163, 0xbfb8aa3b, v126
	v_mul_f32_e32 v167, 0xbfb8aa3b, v127
	v_mul_f32_e32 v170, 0xbfb8aa3b, v128
	v_mul_f32_e32 v171, 0xbfb8aa3b, v129
	v_mul_f32_e32 v172, 0xbfb8aa3b, v122
	v_mul_f32_e32 v173, 0xbfb8aa3b, v123
	v_mul_f32_e32 v174, 0xbfb8aa3b, v124
	v_mul_f32_e32 v175, 0xbfb8aa3b, v125
	v_exp_f32_e32 v163, v163
	v_exp_f32_e32 v167, v167
	v_exp_f32_e32 v170, v170
	v_exp_f32_e32 v171, v171
	v_exp_f32_e32 v172, v172
	v_exp_f32_e32 v173, v173
	v_exp_f32_e32 v174, v174
	v_exp_f32_e32 v175, v175
	v_add_f32_e32 v163, 1.0, v163
	v_add_f32_e32 v167, 1.0, v167
	v_add_f32_e32 v176, 1.0, v170
	v_add_f32_e32 v177, 1.0, v171
	v_add_f32_e32 v178, 1.0, v172
	v_add_f32_e32 v179, 1.0, v173
	v_add_f32_e32 v180, 1.0, v174
	v_add_f32_e32 v181, 1.0, v175
	v_rcp_f32_e32 v170, v163
	v_rcp_f32_e32 v171, v167
	v_rcp_f32_e32 v172, v176
	v_rcp_f32_e32 v173, v177
	v_rcp_f32_e32 v174, v178
	v_rcp_f32_e32 v175, v179
	v_rcp_f32_e32 v176, v180
	v_rcp_f32_e32 v177, v181
	v_pk_mul_f32 v[126:127], v[126:127], v[170:171]
	v_pk_mul_f32 v[128:129], v[128:129], v[172:173]
	v_pk_mul_f32 v[122:123], v[122:123], v[174:175]
	v_pk_mul_f32 v[124:125], v[124:125], v[176:177]
	v_pk_mul_f32 v[118:119], v[118:119], v[126:127]
	v_pk_mul_f32 v[120:121], v[120:121], v[128:129]
	v_pk_mul_f32 v[122:123], v[114:115], v[122:123]
	v_pk_mul_f32 v[124:125], v[116:117], v[124:125]
	v_cvt_pk_bf16_f32 v114, v118, v119
	v_cvt_pk_bf16_f32 v115, v120, v121
	v_cvt_pk_bf16_f32 v116, v122, v123
	v_cvt_pk_bf16_f32 v117, v124, v125
	global_store_dwordx4 v[164:165], v[114:117], off
	s_nop 1
	v_mad_i64_i32 v[116:117], s[8:9], v166, s48, v[148:149]
	v_lshl_add_u64 v[116:117], v[116:117], 0, v[150:151]
	v_or_b32_e32 v114, 32, v152
	v_mov_b32_e32 v120, v233
	v_pk_mul_f32 v[110:111], v[110:111], v[120:121] op_sel_hi:[1,0]
	v_pk_mul_f32 v[112:113], v[112:113], v[120:121] op_sel_hi:[1,0]
	v_pk_mul_f32 v[106:107], v[106:107], v[120:121] op_sel_hi:[1,0]
	v_pk_mul_f32 v[108:109], v[108:109], v[120:121] op_sel_hi:[1,0]
	v_pk_mul_f32 v[102:103], v[102:103], v[120:121] op_sel_hi:[1,0]
	v_pk_mul_f32 v[104:105], v[104:105], v[120:121] op_sel_hi:[1,0]
	v_pk_mul_f32 v[98:99], v[98:99], v[120:121] op_sel_hi:[1,0]
	v_pk_mul_f32 v[100:101], v[100:101], v[120:121] op_sel_hi:[1,0]
	v_mul_f32_e32 v115, 0xbfb8aa3b, v110
	v_mul_f32_e32 v120, 0xbfb8aa3b, v111
	v_mul_f32_e32 v121, 0xbfb8aa3b, v112
	v_mul_f32_e32 v122, 0xbfb8aa3b, v113
	v_mul_f32_e32 v123, 0xbfb8aa3b, v106
	v_mul_f32_e32 v124, 0xbfb8aa3b, v107
	v_mul_f32_e32 v125, 0xbfb8aa3b, v108
	v_mul_f32_e32 v126, 0xbfb8aa3b, v109
	v_exp_f32_e32 v115, v115
	v_exp_f32_e32 v120, v120
	v_exp_f32_e32 v121, v121
	v_exp_f32_e32 v122, v122
	v_exp_f32_e32 v123, v123
	v_exp_f32_e32 v124, v124
	v_exp_f32_e32 v125, v125
	v_exp_f32_e32 v126, v126
	v_add_f32_e32 v115, 1.0, v115
	v_add_f32_e32 v127, 1.0, v120
	v_add_f32_e32 v128, 1.0, v121
	v_add_f32_e32 v129, 1.0, v122
	v_add_f32_e32 v163, 1.0, v123
	v_add_f32_e32 v164, 1.0, v124
	v_add_f32_e32 v165, 1.0, v125
	v_add_f32_e32 v166, 1.0, v126
	v_rcp_f32_e32 v120, v115
	v_rcp_f32_e32 v121, v127
	v_rcp_f32_e32 v122, v128
	v_rcp_f32_e32 v123, v129
	v_rcp_f32_e32 v124, v163
	v_rcp_f32_e32 v125, v164
	v_rcp_f32_e32 v126, v165
	v_rcp_f32_e32 v127, v166
	v_pk_mul_f32 v[110:111], v[110:111], v[120:121]
	v_pk_mul_f32 v[112:113], v[112:113], v[122:123]
	v_pk_mul_f32 v[106:107], v[106:107], v[124:125]
	v_pk_mul_f32 v[108:109], v[108:109], v[126:127]
	v_pk_mul_f32 v[102:103], v[102:103], v[110:111]
	v_pk_mul_f32 v[104:105], v[104:105], v[112:113]
	v_pk_mul_f32 v[106:107], v[98:99], v[106:107]
	v_pk_mul_f32 v[108:109], v[100:101], v[108:109]
	v_cvt_pk_bf16_f32 v98, v102, v103
	v_cvt_pk_bf16_f32 v99, v104, v105
	v_cvt_pk_bf16_f32 v100, v106, v107
	v_cvt_pk_bf16_f32 v101, v108, v109
	global_store_dwordx4 v[116:117], v[98:101], off
	s_nop 1
	v_mad_i64_i32 v[100:101], s[8:9], v114, s48, v[148:149]
	v_lshl_add_u64 v[100:101], v[100:101], 0, v[150:151]
	v_or_b32_e32 v98, 48, v152
	v_mov_b32_e32 v104, v234
	v_pk_mul_f32 v[94:95], v[94:95], v[104:105] op_sel_hi:[1,0]
	v_pk_mul_f32 v[96:97], v[96:97], v[104:105] op_sel_hi:[1,0]
	v_pk_mul_f32 v[90:91], v[90:91], v[104:105] op_sel_hi:[1,0]
	v_pk_mul_f32 v[92:93], v[92:93], v[104:105] op_sel_hi:[1,0]
	v_pk_mul_f32 v[86:87], v[86:87], v[104:105] op_sel_hi:[1,0]
	v_pk_mul_f32 v[88:89], v[88:89], v[104:105] op_sel_hi:[1,0]
	v_pk_mul_f32 v[82:83], v[82:83], v[104:105] op_sel_hi:[1,0]
	v_pk_mul_f32 v[84:85], v[84:85], v[104:105] op_sel_hi:[1,0]
	v_mul_f32_e32 v99, 0xbfb8aa3b, v94
	v_mul_f32_e32 v104, 0xbfb8aa3b, v95
	v_mul_f32_e32 v105, 0xbfb8aa3b, v96
	v_mul_f32_e32 v106, 0xbfb8aa3b, v97
	v_mul_f32_e32 v107, 0xbfb8aa3b, v90
	v_mul_f32_e32 v108, 0xbfb8aa3b, v91
	v_mul_f32_e32 v109, 0xbfb8aa3b, v92
	v_mul_f32_e32 v110, 0xbfb8aa3b, v93
	v_exp_f32_e32 v99, v99
; __device__ __forceinline__ unsigned pk2(float lo, float hi) { const f32x2 v = {lo, hi}; const bf16x2_t b = __builtin_convertvector(v, bf16x2_t); return __builtin_bit_cast(unsigned, b); }
; __device__ __forceinline__ float frcp(float x) { return __builtin_amdgcn_rcpf(x); }
;     __device__ __forceinline__ void operator()(const f32x4 (&acc)[2][2][4][2], const Unit& u, int wr, int wc, int fr, int fq) const {
;         const int row0 = u.pm * 256 + wr * 64 + fr, col0 = u.pn * 128 + wc * 32 + 8 * fq;
; #pragma unroll
;         for (int ai = 0; ai < 2; ++ai)
; #pragma unroll
;             for (int m = 0; m < 4; ++m) {
;                 const int row = row0 + ai * 128 + m * 16; const float rs = row_rstd_q(ssq, row, fq);
;                 float h[8];
; #pragma unroll
;                 for (int n = 0; n < 2; ++n) {
;                     const f32x4 a = acc[ai][0][m][n] * rs, b = acc[ai][1][m][n] * rs;
; #pragma unroll
;                     for (int j = 0; j < 4; ++j) h[4 * n + j] = a[j] * frcp(1.0f + __expf(-a[j])) * b[j];
;                 }
;                 u32x4 w; w.x = pk2(h[0], h[1]); w.y = pk2(h[2], h[3]); w.z = pk2(h[4], h[5]); w.w = pk2(h[6], h[7]);
;                 *(u32x4*)(O + (size_t)row * FF_ + col0) = w;
;             }
	v_exp_f32_e32 v104, v104
	v_exp_f32_e32 v105, v105
	v_exp_f32_e32 v106, v106
	v_exp_f32_e32 v107, v107
	v_exp_f32_e32 v108, v108
	v_exp_f32_e32 v109, v109
	v_exp_f32_e32 v110, v110
	v_add_f32_e32 v99, 1.0, v99
	v_add_f32_e32 v111, 1.0, v104
	v_add_f32_e32 v112, 1.0, v105
	v_add_f32_e32 v113, 1.0, v106
	v_add_f32_e32 v114, 1.0, v107
	v_add_f32_e32 v115, 1.0, v108
	v_add_f32_e32 v116, 1.0, v109
	v_add_f32_e32 v117, 1.0, v110
	v_rcp_f32_e32 v104, v99
	v_rcp_f32_e32 v105, v111
	v_rcp_f32_e32 v106, v112
	v_rcp_f32_e32 v107, v113
	v_rcp_f32_e32 v108, v114
	v_rcp_f32_e32 v109, v115
	v_rcp_f32_e32 v110, v116
	v_rcp_f32_e32 v111, v117
	v_pk_mul_f32 v[94:95], v[94:95], v[104:105]
	v_pk_mul_f32 v[96:97], v[96:97], v[106:107]
	v_pk_mul_f32 v[90:91], v[90:91], v[108:109]
	v_pk_mul_f32 v[92:93], v[92:93], v[110:111]
	v_pk_mul_f32 v[86:87], v[86:87], v[94:95]
	v_pk_mul_f32 v[88:89], v[88:89], v[96:97]
	v_pk_mul_f32 v[90:91], v[82:83], v[90:91]
	v_pk_mul_f32 v[92:93], v[84:85], v[92:93]
	v_cvt_pk_bf16_f32 v82, v86, v87
	v_cvt_pk_bf16_f32 v83, v88, v89
	v_cvt_pk_bf16_f32 v84, v90, v91
	v_cvt_pk_bf16_f32 v85, v92, v93
	global_store_dwordx4 v[100:101], v[82:85], off
	s_nop 1
	v_mad_i64_i32 v[84:85], s[8:9], v98, s48, v[148:149]
	v_lshl_add_u64 v[84:85], v[84:85], 0, v[150:151]
	v_add_u32_e32 v82, 0x80, v152
	v_mov_b32_e32 v88, v235
	v_pk_mul_f32 v[78:79], v[78:79], v[88:89] op_sel_hi:[1,0]
	v_pk_mul_f32 v[80:81], v[80:81], v[88:89] op_sel_hi:[1,0]
	v_pk_mul_f32 v[74:75], v[74:75], v[88:89] op_sel_hi:[1,0]
	v_pk_mul_f32 v[76:77], v[76:77], v[88:89] op_sel_hi:[1,0]
	v_pk_mul_f32 v[70:71], v[70:71], v[88:89] op_sel_hi:[1,0]
	v_pk_mul_f32 v[72:73], v[72:73], v[88:89] op_sel_hi:[1,0]
	v_pk_mul_f32 v[66:67], v[66:67], v[88:89] op_sel_hi:[1,0]
	v_pk_mul_f32 v[68:69], v[68:69], v[88:89] op_sel_hi:[1,0]
	v_mul_f32_e32 v83, 0xbfb8aa3b, v78
	v_mul_f32_e32 v88, 0xbfb8aa3b, v79
	v_mul_f32_e32 v89, 0xbfb8aa3b, v80
	v_mul_f32_e32 v90, 0xbfb8aa3b, v81
	v_mul_f32_e32 v91, 0xbfb8aa3b, v74
	v_mul_f32_e32 v92, 0xbfb8aa3b, v75
	v_mul_f32_e32 v93, 0xbfb8aa3b, v76
	v_mul_f32_e32 v94, 0xbfb8aa3b, v77
	v_exp_f32_e32 v83, v83
	v_exp_f32_e32 v88, v88
	v_exp_f32_e32 v89, v89
	v_exp_f32_e32 v90, v90
	v_exp_f32_e32 v91, v91
	v_exp_f32_e32 v92, v92
	v_exp_f32_e32 v93, v93
	v_exp_f32_e32 v94, v94
	v_add_f32_e32 v83, 1.0, v83
	v_add_f32_e32 v95, 1.0, v88
	v_add_f32_e32 v96, 1.0, v89
	v_add_f32_e32 v97, 1.0, v90
	v_add_f32_e32 v98, 1.0, v91
	v_add_f32_e32 v99, 1.0, v92
	v_add_f32_e32 v100, 1.0, v93
	v_add_f32_e32 v101, 1.0, v94
	v_rcp_f32_e32 v88, v83
	v_rcp_f32_e32 v89, v95
	v_rcp_f32_e32 v90, v96
	v_rcp_f32_e32 v91, v97
	v_rcp_f32_e32 v92, v98
	v_rcp_f32_e32 v93, v99
	v_rcp_f32_e32 v94, v100
	v_rcp_f32_e32 v95, v101
	v_pk_mul_f32 v[78:79], v[78:79], v[88:89]
	v_pk_mul_f32 v[80:81], v[80:81], v[90:91]
	v_pk_mul_f32 v[74:75], v[74:75], v[92:93]
	v_pk_mul_f32 v[76:77], v[76:77], v[94:95]
	v_pk_mul_f32 v[70:71], v[70:71], v[78:79]
	v_pk_mul_f32 v[72:73], v[72:73], v[80:81]
	v_pk_mul_f32 v[74:75], v[66:67], v[74:75]
	v_pk_mul_f32 v[76:77], v[68:69], v[76:77]
	v_cvt_pk_bf16_f32 v66, v70, v71
	v_cvt_pk_bf16_f32 v67, v72, v73
	v_cvt_pk_bf16_f32 v68, v74, v75
	v_cvt_pk_bf16_f32 v69, v76, v77
	global_store_dwordx4 v[84:85], v[66:69], off
	s_nop 1
	v_mad_i64_i32 v[68:69], s[8:9], v82, s48, v[148:149]
	v_lshl_add_u64 v[68:69], v[68:69], 0, v[150:151]
	v_add_u32_e32 v66, 0x90, v152
	v_mov_b32_e32 v72, v236
	v_pk_mul_f32 v[62:63], v[62:63], v[72:73] op_sel_hi:[1,0]
	v_pk_mul_f32 v[64:65], v[64:65], v[72:73] op_sel_hi:[1,0]
	v_pk_mul_f32 v[58:59], v[58:59], v[72:73] op_sel_hi:[1,0]
	v_pk_mul_f32 v[60:61], v[60:61], v[72:73] op_sel_hi:[1,0]
	v_pk_mul_f32 v[54:55], v[54:55], v[72:73] op_sel_hi:[1,0]
	v_pk_mul_f32 v[56:57], v[56:57], v[72:73] op_sel_hi:[1,0]
	v_pk_mul_f32 v[50:51], v[50:51], v[72:73] op_sel_hi:[1,0]
	v_pk_mul_f32 v[52:53], v[52:53], v[72:73] op_sel_hi:[1,0]
	v_mul_f32_e32 v67, 0xbfb8aa3b, v62
	v_mul_f32_e32 v72, 0xbfb8aa3b, v63
	v_mul_f32_e32 v73, 0xbfb8aa3b, v64
	v_mul_f32_e32 v74, 0xbfb8aa3b, v65
	v_mul_f32_e32 v75, 0xbfb8aa3b, v58
	v_mul_f32_e32 v76, 0xbfb8aa3b, v59
	v_mul_f32_e32 v77, 0xbfb8aa3b, v60
	v_mul_f32_e32 v78, 0xbfb8aa3b, v61
	v_exp_f32_e32 v67, v67
	v_exp_f32_e32 v72, v72
	v_exp_f32_e32 v73, v73
	v_exp_f32_e32 v74, v74
	v_exp_f32_e32 v75, v75
	v_exp_f32_e32 v76, v76
	v_exp_f32_e32 v77, v77
	v_exp_f32_e32 v78, v78
	v_add_f32_e32 v67, 1.0, v67
	v_add_f32_e32 v79, 1.0, v72
	v_add_f32_e32 v80, 1.0, v73
	v_add_f32_e32 v81, 1.0, v74
	v_add_f32_e32 v82, 1.0, v75
	v_add_f32_e32 v83, 1.0, v76
	v_add_f32_e32 v84, 1.0, v77
	v_add_f32_e32 v85, 1.0, v78
	v_rcp_f32_e32 v72, v67
	v_rcp_f32_e32 v73, v79
	v_rcp_f32_e32 v74, v80
	v_rcp_f32_e32 v75, v81
	v_rcp_f32_e32 v76, v82
	v_rcp_f32_e32 v77, v83
	v_rcp_f32_e32 v78, v84
	v_rcp_f32_e32 v79, v85
	v_pk_mul_f32 v[62:63], v[62:63], v[72:73]
	v_pk_mul_f32 v[64:65], v[64:65], v[74:75]
	v_pk_mul_f32 v[58:59], v[58:59], v[76:77]
	v_pk_mul_f32 v[60:61], v[60:61], v[78:79]
	v_pk_mul_f32 v[54:55], v[54:55], v[62:63]
	v_pk_mul_f32 v[56:57], v[56:57], v[64:65]
	v_pk_mul_f32 v[58:59], v[50:51], v[58:59]
	v_pk_mul_f32 v[60:61], v[52:53], v[60:61]
	v_cvt_pk_bf16_f32 v50, v54, v55
	v_cvt_pk_bf16_f32 v51, v56, v57
	v_cvt_pk_bf16_f32 v52, v58, v59
	v_cvt_pk_bf16_f32 v53, v60, v61
	global_store_dwordx4 v[68:69], v[50:53], off
	s_nop 1
	v_mad_i64_i32 v[52:53], s[8:9], v66, s48, v[148:149]
	v_lshl_add_u64 v[52:53], v[52:53], 0, v[150:151]
	v_add_u32_e32 v50, 0xa0, v152
	v_mov_b32_e32 v56, v237
	v_pk_mul_f32 v[46:47], v[46:47], v[56:57] op_sel_hi:[1,0]
	v_pk_mul_f32 v[48:49], v[48:49], v[56:57] op_sel_hi:[1,0]
	v_pk_mul_f32 v[42:43], v[42:43], v[56:57] op_sel_hi:[1,0]
; __device__ __forceinline__ unsigned pk2(float lo, float hi) { const f32x2 v = {lo, hi}; const bf16x2_t b = __builtin_convertvector(v, bf16x2_t); return __builtin_bit_cast(unsigned, b); }
; __device__ __forceinline__ float frcp(float x) { return __builtin_amdgcn_rcpf(x); }
;     __device__ __forceinline__ void operator()(const f32x4 (&acc)[2][2][4][2], const Unit& u, int wr, int wc, int fr, int fq) const {
;         const int row0 = u.pm * 256 + wr * 64 + fr, col0 = u.pn * 128 + wc * 32 + 8 * fq;
; #pragma unroll
;         for (int ai = 0; ai < 2; ++ai)
; #pragma unroll
;             for (int m = 0; m < 4; ++m) {
;                 const int row = row0 + ai * 128 + m * 16; const float rs = row_rstd_q(ssq, row, fq);
;                 float h[8];
; #pragma unroll
;                 for (int n = 0; n < 2; ++n) {
;                     const f32x4 a = acc[ai][0][m][n] * rs, b = acc[ai][1][m][n] * rs;
; #pragma unroll
;                     for (int j = 0; j < 4; ++j) h[4 * n + j] = a[j] * frcp(1.0f + __expf(-a[j])) * b[j];
;                 }
;                 u32x4 w; w.x = pk2(h[0], h[1]); w.y = pk2(h[2], h[3]); w.z = pk2(h[4], h[5]); w.w = pk2(h[6], h[7]);
;                 *(u32x4*)(O + (size_t)row * FF_ + col0) = w;
;             }
	v_pk_mul_f32 v[44:45], v[44:45], v[56:57] op_sel_hi:[1,0]
	v_pk_mul_f32 v[38:39], v[38:39], v[56:57] op_sel_hi:[1,0]
	v_pk_mul_f32 v[40:41], v[40:41], v[56:57] op_sel_hi:[1,0]
	v_pk_mul_f32 v[34:35], v[34:35], v[56:57] op_sel_hi:[1,0]
	v_pk_mul_f32 v[36:37], v[36:37], v[56:57] op_sel_hi:[1,0]
	v_mul_f32_e32 v51, 0xbfb8aa3b, v46
	v_mul_f32_e32 v56, 0xbfb8aa3b, v47
	v_mul_f32_e32 v57, 0xbfb8aa3b, v48
	v_mul_f32_e32 v58, 0xbfb8aa3b, v49
	v_mul_f32_e32 v59, 0xbfb8aa3b, v42
	v_mul_f32_e32 v60, 0xbfb8aa3b, v43
	v_mul_f32_e32 v61, 0xbfb8aa3b, v44
	v_mul_f32_e32 v62, 0xbfb8aa3b, v45
	v_exp_f32_e32 v51, v51
	v_exp_f32_e32 v56, v56
	v_exp_f32_e32 v57, v57
	v_exp_f32_e32 v58, v58
	v_exp_f32_e32 v59, v59
	v_exp_f32_e32 v60, v60
	v_exp_f32_e32 v61, v61
	v_exp_f32_e32 v62, v62
	v_add_f32_e32 v51, 1.0, v51
	v_add_f32_e32 v63, 1.0, v56
	v_add_f32_e32 v64, 1.0, v57
	v_add_f32_e32 v65, 1.0, v58
	v_add_f32_e32 v66, 1.0, v59
	v_add_f32_e32 v67, 1.0, v60
	v_add_f32_e32 v68, 1.0, v61
	v_add_f32_e32 v69, 1.0, v62
	v_rcp_f32_e32 v56, v51
	v_rcp_f32_e32 v57, v63
	v_rcp_f32_e32 v58, v64
	v_rcp_f32_e32 v59, v65
	v_rcp_f32_e32 v60, v66
	v_rcp_f32_e32 v61, v67
	v_rcp_f32_e32 v62, v68
	v_rcp_f32_e32 v63, v69
	v_pk_mul_f32 v[46:47], v[46:47], v[56:57]
	v_pk_mul_f32 v[48:49], v[48:49], v[58:59]
	v_pk_mul_f32 v[42:43], v[42:43], v[60:61]
	v_pk_mul_f32 v[44:45], v[44:45], v[62:63]
	v_pk_mul_f32 v[38:39], v[38:39], v[46:47]
	v_pk_mul_f32 v[40:41], v[40:41], v[48:49]
	v_pk_mul_f32 v[42:43], v[34:35], v[42:43]
	v_pk_mul_f32 v[44:45], v[36:37], v[44:45]
	v_cvt_pk_bf16_f32 v34, v38, v39
	v_cvt_pk_bf16_f32 v35, v40, v41
	v_cvt_pk_bf16_f32 v36, v42, v43
	v_cvt_pk_bf16_f32 v37, v44, v45
	global_store_dwordx4 v[52:53], v[34:37], off
	s_nop 1
	v_mad_i64_i32 v[36:37], s[8:9], v50, s48, v[148:149]
	v_lshl_add_u64 v[36:37], v[36:37], 0, v[150:151]
	v_add_u32_e32 v34, 0xb0, v152
	v_mov_b32_e32 v40, v238
	v_pk_mul_f32 v[30:31], v[30:31], v[40:41] op_sel_hi:[1,0]
	v_pk_mul_f32 v[32:33], v[32:33], v[40:41] op_sel_hi:[1,0]
	v_pk_mul_f32 v[26:27], v[26:27], v[40:41] op_sel_hi:[1,0]
	v_pk_mul_f32 v[28:29], v[28:29], v[40:41] op_sel_hi:[1,0]
	v_pk_mul_f32 v[22:23], v[22:23], v[40:41] op_sel_hi:[1,0]
	v_pk_mul_f32 v[24:25], v[24:25], v[40:41] op_sel_hi:[1,0]
	v_pk_mul_f32 v[18:19], v[18:19], v[40:41] op_sel_hi:[1,0]
	v_pk_mul_f32 v[20:21], v[20:21], v[40:41] op_sel_hi:[1,0]
	v_mul_f32_e32 v35, 0xbfb8aa3b, v30
	v_mul_f32_e32 v40, 0xbfb8aa3b, v31
	v_mul_f32_e32 v41, 0xbfb8aa3b, v32
	v_mul_f32_e32 v42, 0xbfb8aa3b, v33
	v_mul_f32_e32 v43, 0xbfb8aa3b, v26
	v_mul_f32_e32 v44, 0xbfb8aa3b, v27
	v_mul_f32_e32 v45, 0xbfb8aa3b, v28
	v_mul_f32_e32 v46, 0xbfb8aa3b, v29
	v_exp_f32_e32 v35, v35
	v_exp_f32_e32 v40, v40
	v_exp_f32_e32 v41, v41
	v_exp_f32_e32 v42, v42
	v_exp_f32_e32 v43, v43
	v_exp_f32_e32 v44, v44
	v_exp_f32_e32 v45, v45
	v_exp_f32_e32 v46, v46
	v_add_f32_e32 v35, 1.0, v35
	v_add_f32_e32 v47, 1.0, v40
	v_add_f32_e32 v48, 1.0, v41
	v_add_f32_e32 v49, 1.0, v42
	v_add_f32_e32 v50, 1.0, v43
	v_add_f32_e32 v51, 1.0, v44
	v_add_f32_e32 v52, 1.0, v45
	v_add_f32_e32 v53, 1.0, v46
	v_rcp_f32_e32 v40, v35
	v_rcp_f32_e32 v41, v47
	v_rcp_f32_e32 v42, v48
	v_rcp_f32_e32 v43, v49
	v_rcp_f32_e32 v44, v50
	v_rcp_f32_e32 v45, v51
	v_rcp_f32_e32 v46, v52
	v_rcp_f32_e32 v47, v53
	v_pk_mul_f32 v[30:31], v[30:31], v[40:41]
	v_pk_mul_f32 v[32:33], v[32:33], v[42:43]
	v_pk_mul_f32 v[26:27], v[26:27], v[44:45]
	v_pk_mul_f32 v[28:29], v[28:29], v[46:47]
	v_pk_mul_f32 v[22:23], v[22:23], v[30:31]
	v_pk_mul_f32 v[24:25], v[24:25], v[32:33]
	v_pk_mul_f32 v[26:27], v[18:19], v[26:27]
	v_pk_mul_f32 v[28:29], v[20:21], v[28:29]
	v_cvt_pk_bf16_f32 v18, v22, v23
	v_cvt_pk_bf16_f32 v19, v24, v25
	v_cvt_pk_bf16_f32 v20, v26, v27
	v_cvt_pk_bf16_f32 v21, v28, v29
	global_store_dwordx4 v[36:37], v[18:21], off
	s_nop 1
	v_mad_i64_i32 v[18:19], s[8:9], v34, s48, v[148:149]
	v_lshl_add_u64 v[18:19], v[18:19], 0, v[150:151]
	v_mov_b32_e32 v20, v239
	v_pk_mul_f32 v[14:15], v[14:15], v[20:21] op_sel_hi:[1,0]
	v_pk_mul_f32 v[16:17], v[16:17], v[20:21] op_sel_hi:[1,0]
	v_pk_mul_f32 v[10:11], v[10:11], v[20:21] op_sel_hi:[1,0]
	v_pk_mul_f32 v[12:13], v[12:13], v[20:21] op_sel_hi:[1,0]
	v_pk_mul_f32 v[6:7], v[6:7], v[20:21] op_sel_hi:[1,0]
	v_pk_mul_f32 v[8:9], v[8:9], v[20:21] op_sel_hi:[1,0]
	v_pk_mul_f32 v[2:3], v[2:3], v[20:21] op_sel_hi:[1,0]
	v_pk_mul_f32 v[4:5], v[4:5], v[20:21] op_sel_hi:[1,0]
	v_mul_f32_e32 v20, 0xbfb8aa3b, v14
	v_mul_f32_e32 v21, 0xbfb8aa3b, v15
	v_mul_f32_e32 v22, 0xbfb8aa3b, v16
	v_mul_f32_e32 v23, 0xbfb8aa3b, v17
	v_mul_f32_e32 v24, 0xbfb8aa3b, v10
	v_mul_f32_e32 v25, 0xbfb8aa3b, v11
	v_mul_f32_e32 v26, 0xbfb8aa3b, v12
	v_mul_f32_e32 v27, 0xbfb8aa3b, v13
	v_exp_f32_e32 v20, v20
	v_exp_f32_e32 v21, v21
	v_exp_f32_e32 v22, v22
	v_exp_f32_e32 v23, v23
	v_exp_f32_e32 v24, v24
	v_exp_f32_e32 v25, v25
	v_exp_f32_e32 v26, v26
	v_exp_f32_e32 v27, v27
	v_add_f32_e32 v20, 1.0, v20
	v_add_f32_e32 v21, 1.0, v21
	v_add_f32_e32 v22, 1.0, v22
	v_add_f32_e32 v23, 1.0, v23
	v_add_f32_e32 v24, 1.0, v24
	v_add_f32_e32 v25, 1.0, v25
	v_add_f32_e32 v26, 1.0, v26
	v_add_f32_e32 v27, 1.0, v27
	v_rcp_f32_e32 v20, v20
	v_rcp_f32_e32 v21, v21
	v_rcp_f32_e32 v22, v22
	v_rcp_f32_e32 v23, v23
	v_rcp_f32_e32 v24, v24
	v_rcp_f32_e32 v25, v25
	v_rcp_f32_e32 v26, v26
	v_rcp_f32_e32 v27, v27
	v_pk_mul_f32 v[14:15], v[14:15], v[20:21]
	v_pk_mul_f32 v[16:17], v[16:17], v[22:23]
	v_pk_mul_f32 v[10:11], v[10:11], v[24:25]
	v_pk_mul_f32 v[12:13], v[12:13], v[26:27]
	v_pk_mul_f32 v[6:7], v[6:7], v[14:15]
	v_pk_mul_f32 v[8:9], v[8:9], v[16:17]
	v_pk_mul_f32 v[10:11], v[2:3], v[10:11]
	v_pk_mul_f32 v[12:13], v[4:5], v[12:13]
	s_andn2_b64 vcc, exec, s[6:7]
	v_cvt_pk_bf16_f32 v2, v6, v7
	v_cvt_pk_bf16_f32 v3, v8, v9
	v_cvt_pk_bf16_f32 v4, v10, v11
	v_cvt_pk_bf16_f32 v5, v12, v13
	s_mov_b64 s[6:7], -1
	global_store_dwordx4 v[18:19], v[2:5], off
	s_nop 1

; __device__ __forceinline__ bf16_t f2bf(float f) { return (bf16_t)(pk2(f, 0.f) & 0xffffu); }
; __device__ __forceinline__ float sigmoidf_(float x) { return frcp(1.0f + __expf(-x)); }
; __device__ __forceinline__ void rwkv_phase_a(const Ctx& C) {
;     ...
; #pragma unroll
;             for (int i = 0; i < 2; ++i) {
;                 const int ch = nc0 + 16 * i; const float w0c = w0[h * 64 + ch], a0c = a0[h * 64 + ch];
; #pragma unroll
;                 for (int j = 0; j < 4; ++j) {
;                     const int t = mt * 16 + 4 * q + j;
;                     FM(0)[t * MS + ch] = -0.60653065971f * sigmoidf_(w0c + aw[i][j]);
;                     FM(1)[t * MS + ch] = sigmoidf_(a0c + aa[i][j]);
;                     Gg[(size_t)(tok0 + t) * GWD_ + h * 64 + ch] = f2bf(ag[i][j]);
;                 }
;             }
;         }
;         __syncthreads();
;         {
;             float ld[8], av[8], kkv[8], k2[8], cl[8];
;             const float kkc = k_k[h * 64 + ci], kac = k_a[h * 64 + ci], rkc = r_k[h * 64 + ci];
.LBB0_721:
	v_readlane_b32 s40, v254, 6
	v_readlane_b32 s54, v254, 20
	v_readlane_b32 s55, v254, 21
	v_mov_b32_e32 v197, v189
	v_readlane_b32 s42, v254, 8
	v_readlane_b32 s43, v254, 9
	v_readlane_b32 s52, v254, 18
	v_readlane_b32 s53, v254, 19
	s_mov_b64 s[66:67], s[54:55]
	v_lshlrev_b64 v[98:99], 2, v[196:197]
	v_readlane_b32 s41, v254, 7
	v_readlane_b32 s46, v254, 12
	v_readlane_b32 s47, v254, 13
	s_mov_b64 s[64:65], s[52:53]
	s_mov_b64 s[54:55], s[42:43]
	s_mov_b64 s[58:59], s[46:47]
	v_lshl_add_u64 v[100:101], s[54:55], 0, v[98:99]
	global_load_dword v114, v[100:101], off
	v_lshl_add_u64 v[98:99], s[58:59], 0, v[98:99]
	global_load_dword v115, v[98:99], off
	global_load_dword v121, v[98:99], off offset:64
	v_lshlrev_b32_e32 v138, 2, v211
	v_or_b32_e32 v122, s56, v209
	v_or_b32_e32 v123, s3, v138
	v_mad_u64_u32 v[112:113], s[14:15], v123, s97, v[122:123]
	global_load_dword v113, v[100:101], off offset:64
	v_lshlrev_b32_e32 v130, 2, v188
	v_readlane_b32 s98, v254, 18
	v_readlane_b32 s99, v254, 19
	v_readlane_b32 s100, v254, 20
	v_readlane_b32 s101, v254, 21
	s_nop 4
	global_load_dword v126, v130, s[98:99]
	global_load_dword v127, v130, s[100:101]
	v_readlane_b32 s98, v254, 42
	v_readlane_b32 s99, v254, 43
	s_nop 4
	global_load_dword v128, v130, s[98:99]
	v_add_u32_e32 v106, s92, v138
	v_ashrrev_i32_e32 v107, 31, v106
	s_add_u32 s22, s26, s18
	v_add_u32_e32 v108, s93, v138
	v_lshlrev_b64 v[100:101], 10, v[106:107]
	s_addc_u32 s23, s27, s19
	v_ashrrev_i32_e32 v109, 31, v108
	v_lshl_or_b32 v100, v122, 1, v100
	v_add_lshl_u32 v118, s56, v209, 1
	v_add_u32_e32 v110, s94, v138
	v_lshlrev_b64 v[98:99], 10, v[108:109]
	v_lshl_add_u64 v[100:101], s[22:23], 0, v[100:101]
	v_ashrrev_i32_e32 v111, 31, v110
	v_or_b32_e32 v98, v98, v118
	v_add_co_u32_e32 v100, vcc, s6, v100
	v_lshlrev_b64 v[106:107], 10, v[110:111]
	v_lshl_add_u64 v[98:99], s[22:23], 0, v[98:99]
	v_addc_co_u32_e32 v101, vcc, 0, v101, vcc
	v_or_b32_e32 v106, v106, v118
	v_add_co_u32_e32 v98, vcc, s6, v98
	v_lshl_add_u64 v[106:107], s[22:23], 0, v[106:107]
	s_nop 0
	v_addc_co_u32_e32 v99, vcc, 0, v99, vcc
	v_cvt_pk_bf16_f32 v116, v182, s0
	v_cvt_pk_bf16_f32 v117, v183, s0
	v_add_co_u32_e32 v106, vcc, s6, v106
	v_cvt_pk_bf16_f32 v119, v184, s0
	s_nop 0
	v_addc_co_u32_e32 v107, vcc, 0, v107, vcc
	global_store_short v[100:101], v116, off
	global_store_short v[98:99], v117, off
	global_store_short v[106:107], v119, off
	v_lshl_add_u32 v112, v112, 2, 0
	v_cvt_pk_bf16_f32 v120, v185, s0
	v_readlane_b32 s44, v254, 10
	v_readlane_b32 s45, v254, 11
	v_readlane_b32 s48, v254, 14
	v_readlane_b32 s49, v254, 15
	v_readlane_b32 s50, v254, 16
	v_readlane_b32 s51, v254, 17
	s_mov_b64 s[52:53], s[40:41]
	v_readlane_b32 s40, v254, 42
	v_readlane_b32 s41, v254, 43
	s_movk_i32 s14, 0x220
	v_readlane_b32 s46, v254, 48
	v_readlane_b32 s47, v254, 49
	v_readlane_b32 s48, v254, 50
	v_readlane_b32 s44, v254, 46
	v_readlane_b32 s45, v254, 47
	v_readlane_b32 s42, v254, 44
	v_readlane_b32 s43, v254, 45
	v_readlane_b32 s49, v254, 51
	v_readlane_b32 s50, v254, 52
	v_readlane_b32 s51, v254, 53
	v_readlane_b32 s52, v254, 54
	v_readlane_b32 s53, v254, 55
	v_readlane_b32 s54, v254, 56
	v_readlane_b32 s55, v254, 57
	s_waitcnt vmcnt(9)
	v_add_f32_e32 v108, v150, v114
	v_add_f32_e32 v110, v151, v114
	s_waitcnt vmcnt(8)
	v_add_f32_e32 v109, v154, v115
	v_mul_f32_e32 v108, 0xbfb8aa3b, v108
	v_mul_f32_e32 v109, 0xbfb8aa3b, v109
	v_mul_f32_e32 v110, 0xbfb8aa3b, v110
	v_exp_f32_e32 v108, v108
	v_exp_f32_e32 v109, v109
	v_exp_f32_e32 v110, v110
	v_add_f32_e32 v111, v155, v115
	v_add_f32_e32 v116, v152, v114
	v_add_f32_e32 v117, v156, v115
	v_mul_f32_e32 v111, 0xbfb8aa3b, v111
	v_mul_f32_e32 v116, 0xbfb8aa3b, v116
	v_mul_f32_e32 v117, 0xbfb8aa3b, v117
	s_waitcnt vmcnt(6)
; __device__ __forceinline__ bf16_t f2bf(float f) { return (bf16_t)(pk2(f, 0.f) & 0xffffu); }
; __device__ __forceinline__ float sigmoidf_(float x) { return frcp(1.0f + __expf(-x)); }
; __device__ __forceinline__ void rwkv_phase_a(const Ctx& C) {
;     ...
; #pragma unroll
;             for (int i = 0; i < 2; ++i) {
;                 const int ch = nc0 + 16 * i; const float w0c = w0[h * 64 + ch], a0c = a0[h * 64 + ch];
; #pragma unroll
;                 for (int j = 0; j < 4; ++j) {
;                     const int t = mt * 16 + 4 * q + j;
;                     FM(0)[t * MS + ch] = -0.60653065971f * sigmoidf_(w0c + aw[i][j]);
;                     FM(1)[t * MS + ch] = sigmoidf_(a0c + aa[i][j]);
;                     Gg[(size_t)(tok0 + t) * GWD_ + h * 64 + ch] = f2bf(ag[i][j]);
;                 }
;             }
;         }
;         __syncthreads();
;         {
;             float ld[8], av[8], kkv[8], k2[8], cl[8];
;             const float kkc = k_k[h * 64 + ci], kac = k_a[h * 64 + ci], rkc = r_k[h * 64 + ci];
;             float run = 0.f;
; #pragma unroll
;             for (int u = 0; u < 8; ++u) {
;                 const int t = tg8 * 8 + u;
;                 ld[u] = FM(0)[t * MS + ci]; av[u] = FM(1)[t * MS + ci];
;                 const float kr = kx[u] * kkc; const float n2 = wave_sum(kr * kr);
;                 kkv[u] = kr * __builtin_amdgcn_rsqf(fmaxf(n2, 1e-24f));
;                 k2[u] = kx[u] * (1.0f + (av[u] - 1.0f) * kac);
;                 const float bs = wave_sum(rr[u] * k2[u] * rkc);
;                 if (lane == 0) bon[(size_t)(tok0 + t) * 8 + h] = bs;
;                 run += ld[u]; cl[u] = run;
	v_add_f32_e32 v102, v102, v113
	v_exp_f32_e32 v111, v111
	v_exp_f32_e32 v116, v116
	v_exp_f32_e32 v117, v117
	v_add_f32_e32 v108, 1.0, v108
	v_mul_f32_e32 v102, 0xbfb8aa3b, v102
	v_add_f32_e32 v109, 1.0, v109
	v_add_f32_e32 v110, 1.0, v110
	v_rcp_f32_e32 v108, v108
	v_exp_f32_e32 v102, v102
	v_rcp_f32_e32 v119, v109
	v_rcp_f32_e32 v109, v110
	v_add_f32_e32 v111, 1.0, v111
	v_add_f32_e32 v116, 1.0, v116
	v_add_f32_e32 v117, 1.0, v117
	v_rcp_f32_e32 v110, v111
	v_rcp_f32_e32 v111, v116
	v_rcp_f32_e32 v116, v117
	v_mul_f32_e32 v117, 0xbf1b4598, v108
	v_add_u32_e32 v108, s95, v138
	v_add_f32_e32 v102, 1.0, v102
	v_mul_f32_e32 v124, 0xbf1b4598, v109
	v_ashrrev_i32_e32 v109, 31, v108
	v_rcp_f32_e32 v102, v102
	v_lshlrev_b64 v[108:109], 10, v[108:109]
	v_or_b32_e32 v108, v108, v118
	v_add_f32_e32 v118, v134, v121
	v_mul_f32_e32 v118, 0xbfb8aa3b, v118
	v_add_f32_e32 v103, v103, v113
	v_exp_f32_e32 v118, v118
	v_mul_f32_e32 v102, 0xbf1b4598, v102
	v_mul_f32_e32 v103, 0xbfb8aa3b, v103
	ds_write2_b32 v112, v117, v102 offset1:16
	v_exp_f32_e32 v103, v103
	v_add_f32_e32 v117, v135, v121
	v_mul_f32_e32 v117, 0xbfb8aa3b, v117
	v_exp_f32_e32 v117, v117
	v_add_f32_e32 v118, 1.0, v118
	v_rcp_f32_e32 v118, v118
	v_add_f32_e32 v103, 1.0, v103
	v_rcp_f32_e32 v103, v103
	v_lshl_add_u64 v[108:109], s[22:23], 0, v[108:109]
	v_add_f32_e32 v117, 1.0, v117
	v_add_co_u32_e32 v108, vcc, s6, v108
	v_add_u32_e32 v102, 0x4400, v112
	v_rcp_f32_e32 v117, v117
	v_addc_co_u32_e32 v109, vcc, 0, v109, vcc
	ds_write2_b32 v102, v119, v118 offset1:16
	v_cvt_pk_bf16_f32 v118, v146, s0
	global_store_short v[108:109], v120, off
	global_store_short v[100:101], v118, off offset:32
	v_mul_f32_e32 v100, 0xbf1b4598, v103
	ds_write2_b32 v112, v124, v100 offset0:68 offset1:84
	ds_write2_b32 v102, v110, v117 offset0:68 offset1:84
	v_add_f32_e32 v100, v104, v113
	v_mul_f32_e32 v100, 0xbfb8aa3b, v100
	v_exp_f32_e32 v100, v100
	v_add_f32_e32 v101, v136, v121
	v_mul_f32_e32 v101, 0xbfb8aa3b, v101
	v_exp_f32_e32 v101, v101
	v_add_f32_e32 v100, 1.0, v100
	v_rcp_f32_e32 v100, v100
	v_cvt_pk_bf16_f32 v103, v147, s0
	v_add_f32_e32 v101, 1.0, v101
	v_rcp_f32_e32 v101, v101
	v_mul_f32_e32 v111, 0xbf1b4598, v111
	global_store_short v[98:99], v103, off offset:32
	v_mul_f32_e32 v98, 0xbf1b4598, v100
	v_add_f32_e32 v114, v153, v114
	ds_write2_b32 v112, v111, v98 offset0:136 offset1:152
	ds_write2_b32 v102, v116, v101 offset0:136 offset1:152
	v_add_f32_e32 v98, v105, v113
	v_mul_f32_e32 v114, 0xbfb8aa3b, v114
	v_mul_f32_e32 v98, 0xbfb8aa3b, v98
	v_add_f32_e32 v115, v157, v115
	v_exp_f32_e32 v114, v114
	v_exp_f32_e32 v98, v98
	v_add_f32_e32 v99, v137, v121
	v_mul_f32_e32 v115, 0xbfb8aa3b, v115
	v_mul_f32_e32 v99, 0xbfb8aa3b, v99
	v_exp_f32_e32 v115, v115
	v_exp_f32_e32 v99, v99
	v_add_f32_e32 v114, 1.0, v114
	v_add_f32_e32 v98, 1.0, v98
	v_rcp_f32_e32 v114, v114
	v_rcp_f32_e32 v98, v98
	v_add_f32_e32 v115, 1.0, v115
	v_add_f32_e32 v99, 1.0, v99
	v_rcp_f32_e32 v115, v115
	v_rcp_f32_e32 v99, v99
	v_mul_f32_e32 v114, 0xbf1b4598, v114
	v_cvt_pk_bf16_f32 v100, v148, s0
	v_mul_f32_e32 v98, 0xbf1b4598, v98
	global_store_short v[106:107], v100, off offset:32
	ds_write2_b32 v112, v114, v98 offset0:204 offset1:220
	ds_write2_b32 v102, v115, v99 offset0:204 offset1:220
	v_cvt_pk_bf16_f32 v98, v149, s0
	global_store_short v[108:109], v98, off offset:32
	v_lshlrev_b64 v[98:99], 2, v[188:189]
	v_lshl_add_u64 v[100:101], s[64:65], 0, v[98:99]
	s_waitcnt lgkmcnt(0)
	s_barrier
	s_waitcnt vmcnt(8)
	v_lshl_add_u64 v[100:101], s[66:67], 0, v[98:99]
	v_mov_b32_e32 v125, v126
	v_lshl_add_u64 v[98:99], s[40:41], 0, v[98:99]
	v_mov_b32_e32 v117, v127
	v_mov_b32_e32 v124, v128
	v_cmp_lt_i32_e32 vcc, 0, v230
	v_lshlrev_b32_e32 v98, 16, v229
	v_and_b32_e32 v99, 0xffff0000, v229
	v_cndmask_b32_e64 v126, 0, 1.0, vcc
	v_fma_f32 v98, v126, v98, -v99
	v_fma_f32 v137, v223, v98, v99
	v_and_b32_e32 v98, 0xffff0000, v219
	v_lshlrev_b32_e32 v102, 16, v228
	v_fma_f32 v98, v126, v98, -v102
	v_fma_f32 v98, v222, v98, v102
	v_mad_u64_u32 v[100:101], s[14:15], v216, s14, v[192:193]
	v_lshl_add_u32 v100, v100, 2, 0
	ds_read2st64_b32 v[100:101], v100 offset1:68
	v_cmp_eq_u32_e32 vcc, 0, v192
	s_nop 0
	v_mul_f32_e32 v127, v98, v125
	v_mul_f32_e32 v103, v127, v127
	s_nop 1
	v_mov_b32_dpp v103, v103 quad_perm:[1,0,3,2] row_mask:0xf bank_mask:0xf
	v_fmac_f32_e32 v103, v127, v127
	v_mov_b32_e32 v104, v103
	s_nop 1
	v_mov_b32_dpp v104, v104 quad_perm:[2,3,0,1] row_mask:0xf bank_mask:0xf
	v_add_f32_e32 v103, v103, v104
	v_mov_b32_e32 v104, v103
	s_nop 1
	v_mov_b32_dpp v104, v104 row_half_mirror row_mask:0xf bank_mask:0xf
	v_add_f32_e32 v103, v103, v104
	v_mov_b32_e32 v104, v103
	s_nop 1
	v_mov_b32_dpp v104, v104 row_mirror row_mask:0xf bank_mask:0xf
	v_add_f32_e32 v103, v103, v104
	s_nop 0
	v_readlane_b32 s21, v103, 0
	v_readlane_b32 s47, v103, 16
	v_readlane_b32 s46, v103, 32
	v_readlane_b32 s48, v103, 48
	s_waitcnt lgkmcnt(0)
	v_add_f32_e32 v103, -1.0, v101
	s_nop 0
	v_fma_f32 v103, v117, v103, 1.0
	v_mul_f32_e32 v98, v98, v103
	v_mul_f32_e32 v103, v137, v98
	s_nop 0
	v_mul_f32_e32 v104, v124, v103
	s_nop 1
	v_mov_b32_dpp v104, v104 quad_perm:[1,0,3,2] row_mask:0xf bank_mask:0xf
	v_fmac_f32_e32 v104, v124, v103
	v_mov_b32_e32 v103, v104
	s_nop 1
	v_mov_b32_dpp v103, v103 quad_perm:[2,3,0,1] row_mask:0xf bank_mask:0xf
	v_add_f32_e32 v103, v104, v103
	v_mov_b32_e32 v104, v103
	s_nop 1
	v_mov_b32_dpp v104, v104 row_half_mirror row_mask:0xf bank_mask:0xf
	v_add_f32_e32 v103, v103, v104
	v_mov_b32_e32 v104, v103
	s_nop 1
	v_mov_b32_dpp v104, v104 row_mirror row_mask:0xf bank_mask:0xf
	v_add_f32_e32 v103, v103, v104
	s_nop 0
	v_readlane_b32 s44, v103, 0
	v_readlane_b32 s14, v103, 16
	v_readlane_b32 s45, v103, 32
	v_readlane_b32 s15, v103, 48
	s_and_saveexec_b64 s[22:23], vcc
	s_cbranch_execz .LBB0_723
	v_add_u32_e32 v104, s31, v212
	v_ashrrev_i32_e32 v105, 31, v104
	s_add_u32 s42, s26, s16
	v_mov_b32_e32 v106, s14
	v_mov_b32_e32 v107, s15
	v_lshlrev_b64 v[104:105], 5, v[104:105]
	s_addc_u32 s43, s27, s17
	v_pk_add_f32 v[106:107], s[44:45], v[106:107]
	v_lshl_add_u64 v[104:105], s[42:43], 0, v[104:105]
	v_add_f32_e32 v103, v106, v107
	global_store_dword v[104:105], v103, off

; __device__ __forceinline__ bf16_t f2bf(float f) { return (bf16_t)(pk2(f, 0.f) & 0xffffu); }
; __device__ __forceinline__ void rwkv_phase_a(const Ctx& C) {
;     ...
;                 const float kr = kx[u] * kkc; const float n2 = wave_sum(kr * kr);
;                 kkv[u] = kr * __builtin_amdgcn_rsqf(fmaxf(n2, 1e-24f));
;                 k2[u] = kx[u] * (1.0f + (av[u] - 1.0f) * kac);
;                 const float bs = wave_sum(rr[u] * k2[u] * rkc);
;                 if (lane == 0) bon[(size_t)(tok0 + t) * 8 + h] = bs;
;                 run += ld[u]; cl[u] = run;
;             }
;             misc[64 + tg8 * 64 + ci] = run;
;             __syncthreads();
;             float pre = 0.f, tot = 0.f;
; #pragma unroll
;             for (int g = 0; g < 8; ++g) { const float v = misc[64 + g * 64 + ci]; tot += v; if (g < tg8) pre += v; }
;             if (tg8 == 0) misc[ci] = __expf(tot);
;             float bh[8], kh[8];
; #pragma unroll
;             for (int u = 0; u < 8; ++u) {
;                 const int t = tg8 * 8 + u; const float cu = cl[u] + pre, cp = cu - ld[u];
;                 const float e_m = __expf(-cu), e_p = __expf(cu), e_t = __expf(tot - cu);
;                 const float at = kkv[u] * __expf(cp);
;                 BM_(0)[t * BS + ci] = f2bf(at); FM(2)[t * MS + ci] = at;
;                 BM_(1)[t * BS + ci] = f2bf(kkv[u] * av[u] * e_m);
;                 BM_(2)[t * BS + ci] = f2bf(k2[u] * e_m);
;                 BM_(3)[t * BS + ci] = f2bf(rr[u] * e_p);
;                 bh[u] = kkv[u] * av[u] * e_t; kh[u] = k2[u] * e_t;
;             }
.LBB0_739:
	s_or_b64 exec, exec, s[22:23]
	v_cmp_lt_i32_e32 vcc, 0, v216
	v_lshlrev_b32_e32 v161, 16, v214
	v_or_b32_e32 v165, s3, v209
	v_cndmask_b32_e32 v160, 0, v160, vcc
	v_add_f32_e32 v159, v159, v160
	v_cmp_lt_i32_e32 vcc, 1, v216
	s_nop 1
	v_cndmask_b32_e32 v159, v160, v159, vcc
	v_add_f32_e32 v158, v158, v159
	v_cmp_lt_i32_e32 vcc, 2, v216
	s_nop 1
	v_cndmask_b32_e32 v158, v159, v158, vcc
	v_add_f32_e32 v157, v157, v158
	v_cmp_lt_i32_e32 vcc, 3, v216
	s_nop 1
	v_cndmask_b32_e32 v157, v158, v157, vcc
	v_add_f32_e32 v156, v156, v157
	v_cmp_lt_i32_e32 vcc, 4, v216
	s_nop 1
	v_cndmask_b32_e32 v156, v157, v156, vcc
	v_add_f32_e32 v135, v135, v156
	v_cmp_lt_i32_e32 vcc, 5, v216
	v_mov_b32_e32 v157, s43
	v_add_f32_e32 v157, s89, v157
	v_cndmask_b32_e32 v135, v156, v135, vcc
	v_add_f32_e32 v134, v134, v135
	v_cmp_lt_i32_e32 vcc, 6, v216
	v_mov_b32_e32 v156, s52
	v_add_f32_e32 v156, s70, v156
	v_cndmask_b32_e32 v134, v135, v134, vcc
	v_add_f32_e32 v124, v124, v134
	v_cmp_lt_i32_e32 vcc, 7, v216
	v_mov_b32_e32 v135, s58
	v_add_f32_e32 v135, s54, v135
	v_cndmask_b32_e32 v164, v134, v124, vcc
	v_mov_b32_e32 v124, s65
	v_mov_b32_e32 v134, s66
	v_add_f32_e32 v124, s59, v124
	v_add_f32_e32 v134, s64, v134
	v_add_f32_e32 v124, v124, v134
	v_mov_b32_e32 v134, s55
	v_add_f32_e32 v134, s53, v134
	v_add_f32_e32 v134, v134, v135
	v_mov_b32_e32 v135, s60
	v_add_f32_e32 v135, s90, v135
	v_add_f32_e32 v135, v135, v156
	v_mov_b32_e32 v156, s42
	v_add_f32_e32 v156, s88, v156
	v_add_f32_e32 v156, v156, v157
	v_max_f32_e32 v124, 0x179abe15, v124
	v_max_f32_e32 v134, 0x179abe15, v134
	v_max_f32_e32 v135, 0x179abe15, v135
	v_max_f32_e32 v156, 0x179abe15, v156
	v_rsq_f32_e32 v124, v124
	v_rsq_f32_e32 v134, v134
	v_rsq_f32_e32 v135, v135
	v_rsq_f32_e32 v156, v156
	v_mul_f32_e32 v125, v125, v124
	v_mul_f32_e32 v124, v133, v134
	v_mul_f32_e32 v135, v132, v135
	v_mul_f32_e32 v134, v131, v156
	v_mov_b32_e32 v131, s14
	v_mov_b32_e32 v132, s15
	v_add_f32_e32 v131, s80, v131
	v_add_f32_e32 v132, s81, v132
	v_add_f32_e32 v131, v131, v132
	v_mov_b32_e32 v132, s78
	v_mov_b32_e32 v133, s79
	v_add_f32_e32 v132, s76, v132
	v_add_f32_e32 v133, s77, v133
	v_add_f32_e32 v132, v132, v133
	v_mov_b32_e32 v133, s74
	v_mov_b32_e32 v156, s75
	v_add_f32_e32 v133, s49, v133
	v_add_f32_e32 v156, s73, v156
	v_add_f32_e32 v133, v133, v156
	v_mov_b32_e32 v156, s47
	v_mov_b32_e32 v157, s48
	v_add_f32_e32 v156, s21, v156
	v_add_f32_e32 v157, s46, v157
	v_add_f32_e32 v156, v156, v157
	v_max_f32_e32 v156, 0x179abe15, v156
	v_max_f32_e32 v133, 0x179abe15, v133
	v_rsq_f32_e32 v158, v156
	v_rsq_f32_e32 v133, v133
	v_max_f32_e32 v131, 0x179abe15, v131
	v_max_f32_e32 v132, 0x179abe15, v132
	v_rsq_f32_e32 v131, v131
	v_rsq_f32_e32 v132, v132
	v_mul_f32_e32 v158, v127, v158
	v_lshlrev_b32_e32 v127, 16, v217
	v_mul_f32_e32 v159, v128, v133
	v_mul_f32_e32 v126, v126, v127
	v_and_b32_e32 v127, 0xffff0000, v217
	v_lshlrev_b32_e32 v128, 16, v213
	v_mov_b32_e32 v162, v127
	v_mov_b32_e32 v163, v128
	v_mul_f32_e32 v157, v130, v131
	v_mul_f32_e32 v156, v129, v132
	v_and_b32_e32 v131, 0xffff0000, v215
	v_lshlrev_b32_e32 v130, 16, v215
	v_and_b32_e32 v129, 0xffff0000, v213
	v_pk_add_f32 v[126:127], v[126:127], v[162:163] neg_lo:[0,1] neg_hi:[0,1]
	v_and_b32_e32 v133, 0xffff0000, v218
	v_pk_fma_f32 v[126:127], v[194:195], v[126:127], v[162:163] op_sel_hi:[0,1,1]
	v_pk_mov_b32 v[162:163], v[128:129], v[130:131] op_sel:[1,0]
	v_lshlrev_b32_e32 v132, 16, v218
	v_pk_add_f32 v[128:129], v[128:129], v[162:163] neg_lo:[0,1] neg_hi:[0,1]
	v_mov_b32_e32 v160, v133
	v_pk_fma_f32 v[128:129], v[194:195], v[128:129], v[162:163] op_sel_hi:[0,1,1]
	v_pk_mov_b32 v[162:163], v[130:131], v[132:133] op_sel:[1,0]
	v_pk_add_f32 v[132:133], v[132:133], v[160:161] neg_lo:[0,1] neg_hi:[0,1]
	v_add_f32_e32 v155, v155, v164
	v_pk_add_f32 v[130:131], v[130:131], v[162:163] neg_lo:[0,1] neg_hi:[0,1]
	v_pk_fma_f32 v[132:133], v[194:195], v[132:133], v[160:161] op_sel_hi:[0,1,1]
	v_sub_f32_e32 v100, v155, v100
	v_mul_f32_e32 v160, 0xbfb8aa3b, v155
	v_pk_fma_f32 v[130:131], v[194:195], v[130:131], v[162:163] op_sel_hi:[0,1,1]
	v_exp_f32_e32 v162, v160
	v_mul_f32_e32 v160, 0x3fb8aa3b, v155
	v_mul_f32_e32 v100, 0x3fb8aa3b, v100
	v_exp_f32_e32 v163, v160
	v_exp_f32_e32 v160, v100
	s_movk_i32 s14, 0x240
	v_mul_lo_u32 v161, v216, s14
	v_or_b32_e32 v161, v161, v192
	v_sub_f32_e32 v100, v149, v155
	v_mul_f32_e32 v155, v158, v160
	v_lshlrev_b32_e32 v166, 1, v161
	v_cvt_pk_bf16_f32 v160, v155, s0
	v_add_u32_e32 v167, 0, v166
	s_movk_i32 s14, 0x880
	ds_write_b16 v167, v160 offset:52224
	v_mad_u64_u32 v[160:161], s[14:15], v216, s14, v[136:137]
	ds_write_b32 v160, v155 offset:34816
	v_mov_b32_e32 v160, v101
	v_mov_b32_e32 v161, v105
	v_pk_mul_f32 v[160:161], v[160:161], v[158:159]
	v_add_u32_e32 v105, s86, v166
	v_mul_f32_e32 v101, v160, v162
	v_cvt_pk_bf16_f32 v101, v101, s0
	ds_write_b16 v167, v101 offset:61440
	v_mul_f32_e32 v101, v98, v162
	v_cvt_pk_bf16_f32 v101, v101, s0
	ds_write_b16 v105, v101
	v_mul_f32_e32 v101, v137, v163
	v_cvt_pk_bf16_f32 v101, v101, s0
	v_add_u32_e32 v105, s87, v166
	ds_write_b16 v105, v101
	v_add_f32_e32 v101, v154, v164
	v_sub_f32_e32 v104, v101, v104
	v_mul_f32_e32 v104, 0x3fb8aa3b, v104
	v_exp_f32_e32 v104, v104
	v_mul_f32_e32 v105, 0xbfb8aa3b, v101
	v_exp_f32_e32 v137, v105
	v_mul_f32_e32 v105, 0x3fb8aa3b, v101
	v_exp_f32_e32 v154, v105
	v_mul_lo_u32 v105, v140, s38
	v_mul_f32_e32 v158, v159, v104
	v_add_lshl_u32 v155, v105, v192, 1
	v_sub_f32_e32 v101, v149, v101
	v_cvt_pk_bf16_f32 v104, v158, s0
	v_add_u32_e32 v159, 0, v155
	v_mul_f32_e32 v100, 0x3fb8aa3b, v100
	v_mul_f32_e32 v101, 0x3fb8aa3b, v101
; #define LAS __attribute__((address_space(3)))
; __device__ __forceinline__ bf16_t f2bf(float f) { return (bf16_t)(pk2(f, 0.f) & 0xffffu); }
; __device__ __forceinline__ u32x4 pack8(const float (&v)[8]) { u32x4 w; w.x = pk2(v[0], v[1]); w.y = pk2(v[2], v[3]); w.z = pk2(v[4], v[5]); w.w = pk2(v[6], v[7]); return w; }
; __device__ __forceinline__ void rwkv_phase_a(const Ctx& C) {
;     ...
;             float bh[8], kh[8];
; #pragma unroll
;             for (int u = 0; u < 8; ++u) {
;                 const int t = tg8 * 8 + u; const float cu = cl[u] + pre, cp = cu - ld[u];
;                 const float e_m = __expf(-cu), e_p = __expf(cu), e_t = __expf(tot - cu);
;                 const float at = kkv[u] * __expf(cp);
;                 BM_(0)[t * BS + ci] = f2bf(at); FM(2)[t * MS + ci] = at;
;                 BM_(1)[t * BS + ci] = f2bf(kkv[u] * av[u] * e_m);
;                 BM_(2)[t * BS + ci] = f2bf(k2[u] * e_m);
;                 BM_(3)[t * BS + ci] = f2bf(rr[u] * e_p);
;                 bh[u] = kkv[u] * av[u] * e_t; kh[u] = k2[u] * e_t;
;             }
;             *(LAS u32x4*)(BM_(4) + ci * BS + tg8 * 8) = pack8(vx);
;             *(LAS u32x4*)(BM_(5) + ci * BS + tg8 * 8) = pack8(bh);
;             *(LAS u32x4*)(BM_(6) + ci * BS + tg8 * 8) = pack8(kh);
;         }
;         __syncthreads();
	ds_write_b16 v159, v104 offset:52224
	v_mad_u64_u32 v[104:105], s[14:15], v140, s39, v[136:137]
	v_exp_f32_e32 v100, v100
	v_exp_f32_e32 v101, v101
	v_mul_f32_e32 v105, v161, v137
	v_cvt_pk_bf16_f32 v105, v105, s0
	ds_write_b16 v159, v105 offset:61440
	v_mul_f32_e32 v105, v99, v137
	v_cvt_pk_bf16_f32 v105, v105, s0
	v_add_u32_e32 v140, s86, v155
	ds_write_b16 v140, v105
	v_mul_f32_e32 v105, v139, v154
	v_add_u32_e32 v139, s87, v155
	v_pk_mul_f32 v[154:155], v[98:99], v[100:101]
	v_add_f32_e32 v98, v153, v164
	v_sub_f32_e32 v99, v98, v106
	v_mul_f32_e32 v99, 0x3fb8aa3b, v99
	v_exp_f32_e32 v99, v99
	v_cvt_pk_bf16_f32 v105, v105, s0
	v_pk_mul_f32 v[136:137], v[160:161], v[100:101]
	v_mul_f32_e32 v100, 0xbfb8aa3b, v98
	ds_write_b16 v139, v105
	v_exp_f32_e32 v105, v100
	v_mul_f32_e32 v100, 0x3fb8aa3b, v98
	v_mul_f32_e32 v99, v156, v99
	v_exp_f32_e32 v106, v100
	v_cvt_pk_bf16_f32 v100, v99, s0
	ds_write_b16 v159, v100 offset:52368
	v_mov_b32_e32 v100, v107
	v_mov_b32_e32 v101, v109
	v_add_u32_e32 v153, 0x8800, v104
	v_pk_mul_f32 v[100:101], v[100:101], v[156:157]
	ds_write2_b32 v153, v158, v99 offset1:68
	v_mul_f32_e32 v99, v100, v105
	v_cvt_pk_bf16_f32 v99, v99, s0
	ds_write_b16 v159, v99 offset:61584
	v_mul_f32_e32 v99, v102, v105
	v_cvt_pk_bf16_f32 v99, v99, s0
	ds_write_b16 v140, v99 offset:144
	v_mul_f32_e32 v99, v141, v106
	v_cvt_pk_bf16_f32 v99, v99, s0
	ds_write_b16 v139, v99 offset:144
	v_add_f32_e32 v99, v152, v164
	v_sub_f32_e32 v105, v99, v108
	v_mul_f32_e32 v105, 0x3fb8aa3b, v105
	v_exp_f32_e32 v105, v105
	v_mul_f32_e32 v106, 0xbfb8aa3b, v99
	v_exp_f32_e32 v106, v106
	v_mul_f32_e32 v107, 0x3fb8aa3b, v99
	v_sub_f32_e32 v98, v149, v98
	v_exp_f32_e32 v107, v107
	v_sub_f32_e32 v99, v149, v99
	v_mul_f32_e32 v105, v157, v105
	v_mul_f32_e32 v98, 0x3fb8aa3b, v98
	v_mul_f32_e32 v99, 0x3fb8aa3b, v99
	v_cvt_pk_bf16_f32 v108, v105, s0
	v_exp_f32_e32 v98, v98
	v_exp_f32_e32 v99, v99
	ds_write_b16 v159, v108 offset:52512
	v_mul_f32_e32 v108, v101, v106
	v_mul_f32_e32 v106, v103, v106
	v_cvt_pk_bf16_f32 v106, v106, s0
	ds_write_b16 v140, v106 offset:288
	v_mul_f32_e32 v106, v142, v107
	v_cvt_pk_bf16_f32 v106, v106, s0
	ds_write_b16 v139, v106 offset:288
	v_pk_mul_f32 v[106:107], v[100:101], v[98:99]
	v_pk_mul_f32 v[102:103], v[102:103], v[98:99]
	v_add_f32_e32 v98, v151, v164
	v_sub_f32_e32 v99, v98, v112
	v_mul_f32_e32 v99, 0x3fb8aa3b, v99
	v_exp_f32_e32 v99, v99
	v_cvt_pk_bf16_f32 v108, v108, s0
	v_mul_f32_e32 v100, 0xbfb8aa3b, v98
	ds_write_b16 v159, v108 offset:61728
	v_exp_f32_e32 v108, v100
	v_mul_f32_e32 v100, 0x3fb8aa3b, v98
	v_mul_f32_e32 v99, v134, v99
	v_exp_f32_e32 v109, v100
	v_cvt_pk_bf16_f32 v100, v99, s0
	ds_write_b16 v159, v100 offset:52656
	ds_write2_b32 v153, v105, v99 offset0:136 offset1:204
	v_mov_b32_e32 v100, v113
	v_mov_b32_e32 v101, v115
	v_pk_mul_f32 v[100:101], v[100:101], v[134:135]
	v_sub_f32_e32 v98, v149, v98
	v_mul_f32_e32 v99, v100, v108
	v_cvt_pk_bf16_f32 v99, v99, s0
	ds_write_b16 v159, v99 offset:61872
	v_mul_f32_e32 v99, v110, v108
	v_cvt_pk_bf16_f32 v99, v99, s0
	ds_write_b16 v140, v99 offset:432
	v_mul_f32_e32 v99, v143, v109
	v_cvt_pk_bf16_f32 v99, v99, s0
	ds_write_b16 v139, v99 offset:432
	v_add_f32_e32 v99, v150, v164
	v_sub_f32_e32 v105, v99, v114
	v_mul_f32_e32 v105, 0x3fb8aa3b, v105
	v_exp_f32_e32 v105, v105
	v_mul_f32_e32 v108, 0xbfb8aa3b, v99
	v_exp_f32_e32 v108, v108
	v_mul_f32_e32 v109, 0x3fb8aa3b, v99
	v_exp_f32_e32 v109, v109
	v_sub_f32_e32 v99, v149, v99
	v_mul_f32_e32 v105, v135, v105
	v_mul_f32_e32 v98, 0x3fb8aa3b, v98
	v_mul_f32_e32 v99, 0x3fb8aa3b, v99
	v_cvt_pk_bf16_f32 v112, v105, s0
	v_exp_f32_e32 v98, v98
	v_exp_f32_e32 v99, v99
	ds_write_b16 v159, v112 offset:52800
	v_mul_f32_e32 v112, v101, v108
	v_mul_f32_e32 v108, v111, v108
	v_cvt_pk_bf16_f32 v108, v108, s0
	ds_write_b16 v140, v108 offset:576
	v_mul_f32_e32 v108, v144, v109
	v_cvt_pk_bf16_f32 v108, v108, s0
	ds_write_b16 v139, v108 offset:576
	v_pk_mul_f32 v[108:109], v[100:101], v[98:99]
	v_pk_mul_f32 v[110:111], v[110:111], v[98:99]
	v_add_f32_e32 v98, v148, v164
	v_sub_f32_e32 v99, v98, v118
	v_mul_f32_e32 v99, 0x3fb8aa3b, v99
	v_exp_f32_e32 v99, v99
	v_cvt_pk_bf16_f32 v112, v112, s0
	v_mul_f32_e32 v100, 0xbfb8aa3b, v98
	ds_write_b16 v159, v112 offset:62016
	v_exp_f32_e32 v112, v100
	v_mul_f32_e32 v100, 0x3fb8aa3b, v98
	v_mul_f32_e32 v99, v124, v99
	v_exp_f32_e32 v113, v100
	v_cvt_pk_bf16_f32 v100, v99, s0
	ds_write_b16 v159, v100 offset:52944
	v_add_u32_e32 v100, 0x8c00, v104
	ds_write2_b32 v100, v105, v99 offset0:16 offset1:84
	v_mov_b32_e32 v100, v119
	v_mov_b32_e32 v101, v121
	v_pk_mul_f32 v[100:101], v[100:101], v[124:125]
	v_sub_f32_e32 v98, v149, v98
	v_mul_f32_e32 v99, v100, v112
	v_cvt_pk_bf16_f32 v99, v99, s0
	ds_write_b16 v159, v99 offset:62160
	v_mul_f32_e32 v99, v116, v112
	v_cvt_pk_bf16_f32 v99, v99, s0
	ds_write_b16 v140, v99 offset:720
	v_mul_f32_e32 v99, v145, v113
	v_cvt_pk_bf16_f32 v99, v99, s0
	ds_write_b16 v139, v99 offset:720
	v_add_f32_e32 v99, v147, v164
	v_sub_f32_e32 v105, v99, v120
	v_mul_f32_e32 v105, 0x3fb8aa3b, v105
	v_exp_f32_e32 v105, v105
	v_mul_f32_e32 v112, 0xbfb8aa3b, v99
	v_exp_f32_e32 v112, v112
	v_mul_f32_e32 v113, 0x3fb8aa3b, v99
	v_mul_f32_e32 v105, v125, v105
	v_cvt_pk_bf16_f32 v114, v105, s0
	v_exp_f32_e32 v113, v113
	v_sub_f32_e32 v99, v149, v99
	ds_write_b16 v159, v114 offset:53088
	ds_write_b32 v104, v105 offset:36448
	v_mul_f32_e32 v104, v101, v112
	v_mul_f32_e32 v98, 0x3fb8aa3b, v98
	v_mul_f32_e32 v99, 0x3fb8aa3b, v99
	v_cvt_pk_bf16_f32 v104, v104, s0
	v_exp_f32_e32 v98, v98
	v_exp_f32_e32 v99, v99
	ds_write_b16 v159, v104 offset:62304
	v_mul_f32_e32 v104, v117, v112
	v_cvt_pk_bf16_f32 v104, v104, s0
	ds_write_b16 v140, v104 offset:864
	v_mul_f32_e32 v104, v146, v113
	v_mul_u32_u24_e32 v114, 0x48, v192
	v_cvt_pk_bf16_f32 v104, v104, s0
	v_lshlrev_b32_e32 v114, 1, v114
	v_lshlrev_b32_e32 v115, 1, v212
	ds_write_b16 v139, v104 offset:864
	v_pk_mul_f32 v[104:105], v[100:101], v[98:99]
	v_pk_mul_f32 v[112:113], v[116:117], v[98:99]
	v_cvt_pk_bf16_f32 v98, v126, v127
	v_cvt_pk_bf16_f32 v99, v128, v129
	v_cvt_pk_bf16_f32 v100, v130, v131
	v_cvt_pk_bf16_f32 v101, v132, v133
	v_add3_u32 v116, s34, v114, v115
	ds_write_b128 v116, v[98:101]
	v_cvt_pk_bf16_f32 v98, v136, v137
	v_cvt_pk_bf16_f32 v99, v106, v107
	v_cvt_pk_bf16_f32 v100, v108, v109
	v_cvt_pk_bf16_f32 v101, v104, v105
	v_add3_u32 v104, s35, v114, v115
	ds_write_b128 v104, v[98:101]
	v_cvt_pk_bf16_f32 v98, v154, v155
	v_cvt_pk_bf16_f32 v99, v102, v103
	v_cvt_pk_bf16_f32 v100, v110, v111
	v_cvt_pk_bf16_f32 v101, v112, v113
	v_add3_u32 v102, s36, v114, v115
	v_mul_lo_u32 v131, v165, s37
	ds_write_b128 v102, v[98:101]
	v_add3_u32 v102, 0, v131, v190
	s_waitcnt lgkmcnt(0)
	s_barrier
; #define LAS __attribute__((address_space(3)))
; __device__ __forceinline__ bf16_t f2bf(float f) { return (bf16_t)(pk2(f, 0.f) & 0xffffu); }
; #define ZACC(a) do { a[0] = (f32x4){0.f, 0.f, 0.f, 0.f}; a[1] = (f32x4){0.f, 0.f, 0.f, 0.f}; } while (0)
; __device__ __forceinline__ void mmb(f32x4 (&acc)[2], const LAS bf16_t* A, const LAS bf16_t* B, int mrow, int nc0, int q) {
; #pragma unroll
;     for (int ks = 0; ks < 2; ++ks) {
;         const bf16x8 a = *(const LAS bf16x8*)(A + mrow * BS + ks * 32 + q * 8);
;         const bf16x8 b0 = *(const LAS bf16x8*)(B + nc0 * BS + ks * 32 + q * 8), b1 = *(const LAS bf16x8*)(B + (nc0 + 16) * BS + ks * 32 + q * 8);
;         acc[0] = __builtin_amdgcn_mfma_f32_16x16x32_bf16(a, b0, acc[0], 0, 0, 0);
;         acc[1] = __builtin_amdgcn_mfma_f32_16x16x32_bf16(a, b1, acc[1], 0, 0, 0);
;     }
; }
; __device__ __forceinline__ void rwkv_phase_a(const Ctx& C) {
;     ...
;         {
;             f32x4 x1[2], x2[2], x3[2], x4[2]; ZACC(x1); ZACC(x2); ZACC(x3); ZACC(x4);
;             mmb(x1, BM_(0), BM_(2), mrow, nc0, q);
;             mmb(x2, BM_(0), BM_(1), mrow, nc0, q);
;             mmb(x3, BM_(3), BM_(1), mrow, nc0, q);
;             mmb(x4, BM_(3), BM_(2), mrow, nc0, q);
; #pragma unroll
;             for (int i = 0; i < 2; ++i)
; #pragma unroll
;                 for (int j = 0; j < 4; ++j) { const int r = mt * 16 + 4 * q + j, cc = nc0 + 16 * i;
;                     BM_(7)[r * BS + cc] = f2bf(r > cc ? x1[i][j] : 0.f); FM(0)[r * MS + cc] = r > cc ? x2[i][j] : 0.f;
;                     BM_(8)[r * BS + cc] = f2bf(r >= cc ? x3[i][j] : 0.f); BM_(9)[r * BS + cc] = f2bf(r >= cc ? x4[i][j] : 0.f); }
;         }
;         __syncthreads();
	ds_read_b128 v[98:101], v102 offset:52224
	v_mul_u32_u24_e32 v110, 0x90, v122
	v_add3_u32 v103, s86, v110, v190
	ds_read_b128 v[104:107], v103
	ds_read_b128 v[112:115], v102 offset:52288
	ds_read_b128 v[116:119], v103 offset:64
	ds_read_b128 v[134:137], v103 offset:2304
	ds_read_b128 v[140:143], v103 offset:2368
	v_mad_u32_u24 v103, v122, s37, 0
	v_add_u32_e32 v132, v103, v190
	ds_read_b128 v[148:151], v132 offset:61440
	ds_read_b128 v[152:155], v132 offset:61504
	ds_read_b128 v[160:163], v132 offset:63744
	ds_read_b128 v[164:167], v132 offset:63808
	s_waitcnt lgkmcnt(8)
	v_mfma_f32_16x16x32_bf16 v[124:127], v[98:101], v[104:107], 0
	v_add3_u32 v108, s87, v131, v190
	v_mul_lo_u32 v109, v123, s38
	v_cmp_gt_u32_e32 vcc, v123, v122
	s_waitcnt lgkmcnt(5)
	v_mfma_f32_16x16x32_bf16 v[144:147], v[98:101], v[134:137], 0
	v_add_lshl_u32 v111, v109, v122, 1
	s_movk_i32 s14, 0xff74
	v_mad_i32_i24 v103, v122, s14, v103
	s_waitcnt lgkmcnt(3)
	v_mfma_f32_16x16x32_bf16 v[156:159], v[98:101], v[148:151], 0
	v_or_b32_e32 v130, 16, v122
	v_add3_u32 v133, s34, v110, v190
	s_waitcnt lgkmcnt(1)
	v_mfma_f32_16x16x32_bf16 v[98:101], v[98:101], v[160:163], 0
	v_mfma_f32_16x16x32_bf16 v[124:127], v[112:115], v[116:119], v[124:127]
	v_mfma_f32_16x16x32_bf16 v[144:147], v[112:115], v[140:143], v[144:147]
	v_mfma_f32_16x16x32_bf16 v[156:159], v[112:115], v[152:155], v[156:159]
	s_waitcnt lgkmcnt(0)
	v_mfma_f32_16x16x32_bf16 v[98:101], v[112:115], v[164:167], v[98:101]
	ds_read_b128 v[112:115], v108
	ds_read_b128 v[168:171], v108 offset:64
	s_nop 1
	v_cvt_pk_bf16_f32 v108, v124, s0
	v_cndmask_b32_e32 v108, 0, v108, vcc
	s_waitcnt lgkmcnt(1)
	v_mfma_f32_16x16x32_bf16 v[148:151], v[112:115], v[148:151], 0
	v_lshl_add_u32 v124, v122, 2, 0
	v_mfma_f32_16x16x32_bf16 v[104:107], v[112:115], v[104:107], 0
	s_waitcnt lgkmcnt(0)
	v_mfma_f32_16x16x32_bf16 v[148:151], v[168:171], v[152:155], v[148:151]
	v_mfma_f32_16x16x32_bf16 v[104:107], v[168:171], v[116:119], v[104:107]
	v_add_u32_e32 v116, s91, v111
	ds_write_b16 v116, v108
	v_mul_lo_u32 v116, v123, s39
	v_cndmask_b32_e32 v108, 0, v156, vcc
	v_add_u32_e32 v117, v103, v116
	ds_write_b32 v117, v108
	s_nop 0
	v_cvt_pk_bf16_f32 v108, v148, s0
	v_cmp_lt_u32_e32 vcc, v123, v122
	v_cvt_pk_bf16_f32 v104, v104, s0
	v_add_u32_e32 v117, s2, v111
	v_cndmask_b32_e64 v108, v108, 0, vcc
	v_cndmask_b32_e64 v104, v104, 0, vcc
	ds_write_b16 v117, v108
	v_add_u32_e32 v108, s68, v111
	ds_write_b16 v108, v104
	v_add_u32_e32 v108, 0x48, v109
	v_cvt_pk_bf16_f32 v104, v125, s0
	v_add_lshl_u32 v111, v108, v122, 1
	v_cndmask_b32_e64 v104, v104, 0, vcc
	v_add_u32_e32 v117, s91, v111
	ds_write_b16 v117, v104
	v_add_u32_e32 v117, 0x110, v116
	v_mfma_f32_16x16x32_bf16 v[160:163], v[112:115], v[160:163], 0
	v_cndmask_b32_e64 v104, v157, 0, vcc
	v_add_u32_e32 v118, v103, v117
	ds_write_b32 v118, v104
	v_mfma_f32_16x16x32_bf16 v[112:115], v[112:115], v[134:137], 0
	v_or_b32_e32 v136, 1, v123
	v_cvt_pk_bf16_f32 v104, v149, s0
	v_cmp_lt_u32_e32 vcc, v136, v122
	v_cvt_pk_bf16_f32 v105, v105, s0
	v_add_u32_e32 v118, s2, v111
	v_cndmask_b32_e64 v104, v104, 0, vcc
	v_cndmask_b32_e64 v105, v105, 0, vcc
	ds_write_b16 v118, v104
	v_add_u32_e32 v104, s68, v111
	v_or_b32_e32 v135, 2, v123
	ds_write_b16 v104, v105
	v_add_u32_e32 v105, 0x90, v109
	v_cvt_pk_bf16_f32 v104, v126, s0
	v_cmp_gt_u32_e32 vcc, v135, v122
	v_add_lshl_u32 v111, v105, v122, 1
	v_add_u32_e32 v118, s91, v111
	v_cndmask_b32_e32 v104, 0, v104, vcc
	ds_write_b16 v118, v104
	v_add_u32_e32 v118, 0x220, v116
	v_cndmask_b32_e32 v104, 0, v158, vcc
	v_add_u32_e32 v119, v103, v118
	ds_write_b32 v119, v104
	v_cvt_pk_bf16_f32 v104, v150, s0
	v_cmp_lt_u32_e32 vcc, v135, v122
	v_cvt_pk_bf16_f32 v106, v106, s0
	v_add_u32_e32 v119, s2, v111
	v_cndmask_b32_e64 v104, v104, 0, vcc
	v_cndmask_b32_e64 v106, v106, 0, vcc
	ds_write_b16 v119, v104
	v_add_u32_e32 v104, s68, v111
	v_or_b32_e32 v134, 3, v123
	ds_write_b16 v104, v106
	v_add_u32_e32 v106, 0xd8, v109
	v_cvt_pk_bf16_f32 v104, v127, s0
	v_cmp_gt_u32_e32 vcc, v134, v122
	v_add_lshl_u32 v111, v106, v122, 1
	v_add_u32_e32 v119, s91, v111
	v_cndmask_b32_e32 v104, 0, v104, vcc
	ds_write_b16 v119, v104
	v_add_u32_e32 v119, 0x330, v116
	v_cndmask_b32_e32 v104, 0, v159, vcc
	v_add_u32_e32 v103, v103, v119
	ds_write_b32 v103, v104
	v_cvt_pk_bf16_f32 v103, v151, s0
	v_cmp_lt_u32_e32 vcc, v134, v122
	v_cvt_pk_bf16_f32 v104, v107, s0
	v_add_u32_e32 v107, s2, v111
	v_cndmask_b32_e64 v103, v103, 0, vcc
	v_mfma_f32_16x16x32_bf16 v[152:155], v[168:171], v[164:167], v[160:163]
	v_cndmask_b32_e64 v104, v104, 0, vcc
	ds_write_b16 v107, v103
	v_add_u32_e32 v103, s68, v111
	v_mfma_f32_16x16x32_bf16 v[112:115], v[168:171], v[140:143], v[112:115]
	ds_write_b16 v103, v104
	v_cvt_pk_bf16_f32 v103, v144, s0
	v_cmp_gt_u32_e32 vcc, v123, v130
	v_add_lshl_u32 v104, v109, v130, 1
	v_add_u32_e32 v107, s91, v104
	v_cndmask_b32_e32 v103, 0, v103, vcc
	ds_write_b16 v107, v103
	v_cndmask_b32_e32 v98, 0, v98, vcc
	v_add_u32_e32 v103, v124, v116
	ds_write_b32 v103, v98 offset:64
	v_cvt_pk_bf16_f32 v98, v152, s0
	v_cmp_lt_u32_e32 vcc, v123, v130
	v_cvt_pk_bf16_f32 v107, v112, s0
	v_add_u32_e32 v109, s2, v104
	v_cndmask_b32_e64 v98, v98, 0, vcc
	v_cndmask_b32_e64 v107, v107, 0, vcc
	ds_write_b16 v109, v98
	v_add_u32_e32 v98, s68, v104
	ds_write_b16 v98, v107
	v_cvt_pk_bf16_f32 v98, v145, s0
	v_add_lshl_u32 v104, v108, v130, 1
	v_cndmask_b32_e64 v98, v98, 0, vcc
	v_add_u32_e32 v107, s91, v104
	ds_write_b16 v107, v98
	v_cndmask_b32_e64 v98, v99, 0, vcc
	v_add_u32_e32 v108, v124, v117
	ds_write_b32 v108, v98 offset:64
	v_cvt_pk_bf16_f32 v98, v153, s0
	v_cmp_lt_u32_e32 vcc, v136, v130
	v_cvt_pk_bf16_f32 v99, v113, s0
	v_add_u32_e32 v107, s2, v104
	v_cndmask_b32_e64 v98, v98, 0, vcc
	v_cndmask_b32_e64 v99, v99, 0, vcc
	ds_write_b16 v107, v98
	v_add_u32_e32 v98, s68, v104
	ds_write_b16 v98, v99
	v_cvt_pk_bf16_f32 v98, v146, s0
	v_cmp_gt_u32_e32 vcc, v135, v130
	v_add_lshl_u32 v99, v105, v130, 1
	v_add_u32_e32 v104, s91, v99
	v_cndmask_b32_e32 v98, 0, v98, vcc
	ds_write_b16 v104, v98
	v_cndmask_b32_e32 v98, 0, v100, vcc
	v_add_u32_e32 v109, v124, v118
	ds_write_b32 v109, v98 offset:64
	v_cvt_pk_bf16_f32 v98, v154, s0
	v_cmp_lt_u32_e32 vcc, v135, v130
	v_cvt_pk_bf16_f32 v100, v114, s0
	v_add_u32_e32 v104, s2, v99
	v_cndmask_b32_e64 v98, v98, 0, vcc
	v_cndmask_b32_e64 v100, v100, 0, vcc
	ds_write_b16 v104, v98
	v_add_u32_e32 v98, s68, v99
	ds_write_b16 v98, v100
	v_cvt_pk_bf16_f32 v98, v147, s0
	v_cmp_gt_u32_e32 vcc, v134, v130
	v_add_lshl_u32 v99, v106, v130, 1
	v_add_u32_e32 v100, s91, v99
	v_cndmask_b32_e32 v98, 0, v98, vcc
	ds_write_b16 v100, v98
	v_cndmask_b32_e32 v98, 0, v101, vcc
	v_add_u32_e32 v111, v124, v119
	ds_write_b32 v111, v98 offset:64
	v_cvt_pk_bf16_f32 v98, v155, s0
	v_cmp_lt_u32_e32 vcc, v134, v130
	v_cvt_pk_bf16_f32 v100, v115, s0
	v_add_u32_e32 v101, s2, v99
	v_cndmask_b32_e64 v98, v98, 0, vcc
	v_cndmask_b32_e64 v100, v100, 0, vcc
	ds_write_b16 v101, v98
	v_add_u32_e32 v98, s68, v99
	v_add3_u32 v112, s91, v131, v190
	ds_write_b16 v98, v100
	s_waitcnt lgkmcnt(0)
; #define LAS __attribute__((address_space(3)))
; #define ZACC(a) do { a[0] = (f32x4){0.f, 0.f, 0.f, 0.f}; a[1] = (f32x4){0.f, 0.f, 0.f, 0.f}; } while (0)
; __device__ __forceinline__ void rwkv_phase_a(const Ctx& C) {
;     ...
;         {
;             f32x4 x1[2]; ZACC(x1);
;             mmb(x1, BM_(7), BM_(4), mrow, nc0, q);
; #pragma unroll
;             for (int i = 0; i < 2; ++i)
; #pragma unroll
;                 for (int j = 0; j < 4; ++j) { const int r = mt * 16 + 4 * q + j, cc = nc0 + 16 * i; FM(1)[r * MS + cc] = x1[i][j]; }
;             if (tid < 64) {
;                 const int blk = tid >> 4, col = tid & 15; const LAS float* L = FM(0) + (blk * 16) * MS + blk * 16;
;                 float x[16];
; #pragma unroll
;                 for (int r = 0; r < 16; ++r) {
;                     float a = (r == col) ? 1.f : 0.f;
; #pragma unroll
;                     for (int s2 = 0; s2 < r; ++s2) a -= L[r * MS + s2] * x[s2];
;                     x[r] = a;
;                 }
; #pragma unroll
;                 for (int r = 0; r < 16; ++r) DI[(blk * 16 + r) * 20 + col] = x[r];
;             }
	s_barrier
	ds_read_b128 v[98:101], v112
	ds_read_b128 v[104:107], v133
	ds_read_b128 v[112:115], v112 offset:64
	ds_read_b128 v[116:119], v133 offset:64
	ds_read_b128 v[126:129], v133 offset:2304
	ds_read_b128 v[140:143], v133 offset:2368
	s_waitcnt lgkmcnt(4)
	v_mfma_f32_16x16x32_bf16 v[104:107], v[98:101], v[104:107], 0
	v_add_u32_e32 v103, 0x4400, v103
	v_cmp_gt_i32_e32 vcc, 64, v210
	s_waitcnt lgkmcnt(1)
	v_mfma_f32_16x16x32_bf16 v[98:101], v[98:101], v[126:129], 0
	v_mfma_f32_16x16x32_bf16 v[104:107], v[112:115], v[116:119], v[104:107]
	s_waitcnt lgkmcnt(0)
	v_mfma_f32_16x16x32_bf16 v[98:101], v[112:115], v[140:143], v[98:101]
	s_nop 7
	ds_write2_b32 v103, v104, v98 offset1:16
	v_add_u32_e32 v98, 0x4400, v108
	ds_write2_b32 v98, v105, v99 offset1:16
	v_add_u32_e32 v98, 0x4400, v109
	ds_write2_b32 v98, v106, v100 offset1:16
	v_add_u32_e32 v98, 0x4400, v111
	ds_write2_b32 v98, v107, v101 offset1:16
	s_and_saveexec_b64 s[22:23], vcc
	s_cbranch_execz .LBB0_741
	v_and_b32_e32 v98, -16, v210
	v_mul_lo_u32 v121, v98, s39
	v_lshl_add_u32 v121, v98, 2, v121
	s_movk_i32 s21, 0x50
	ds_read_b128 v[140:143], v121 offset:272
	ds_read_b128 v[144:147], v121 offset:544
	ds_read_b128 v[148:151], v121 offset:816
	ds_read_b128 v[152:155], v121 offset:1088
	ds_read_b128 v[156:159], v121 offset:1360
	ds_read_b128 v[160:163], v121 offset:1376
	ds_read_b128 v[164:167], v121 offset:1632
	ds_read_b128 v[168:171], v121 offset:1648
	ds_read_b128 v[172:175], v121 offset:1904
	ds_read_b128 v[176:179], v121 offset:1920
	ds_read_b128 v[180:183], v121 offset:2176
	ds_read_b128 v[228:231], v121 offset:2192
	v_cmp_eq_u32_e32 vcc, 0, v209
	v_cmp_eq_u32_e64 s[14:15], 1, v209
	s_nop 0
	v_cndmask_b32_e64 v99, 0, 1.0, vcc
	v_cndmask_b32_e64 v100, 0, 1.0, s[14:15]
	v_cmp_eq_u32_e32 vcc, 2, v209
	v_cmp_eq_u32_e64 s[14:15], 3, v209
	s_nop 0
	v_cndmask_b32_e64 v103, 0, 1.0, vcc
	v_cndmask_b32_e64 v104, 0, 1.0, s[14:15]
	v_cmp_eq_u32_e32 vcc, 4, v209
	v_cmp_eq_u32_e64 s[14:15], 5, v209
	s_nop 0
	v_cndmask_b32_e64 v105, 0, 1.0, vcc
	v_cndmask_b32_e64 v106, 0, 1.0, s[14:15]
	v_cmp_eq_u32_e32 vcc, 6, v209
	v_cmp_eq_u32_e64 s[14:15], 7, v209
	s_nop 0
	v_cndmask_b32_e64 v107, 0, 1.0, vcc
	v_cndmask_b32_e64 v108, 0, 1.0, s[14:15]
	v_cmp_eq_u32_e32 vcc, 8, v209
	v_cmp_eq_u32_e64 s[14:15], 9, v209
	s_nop 0
	v_cndmask_b32_e64 v109, 0, 1.0, vcc
	v_cndmask_b32_e64 v111, 0, 1.0, s[14:15]
	v_cmp_eq_u32_e32 vcc, 10, v209
	v_cmp_eq_u32_e64 s[14:15], 11, v209
	s_nop 0
	v_cndmask_b32_e64 v112, 0, 1.0, vcc
	v_cndmask_b32_e64 v113, 0, 1.0, s[14:15]
	v_cmp_eq_u32_e32 vcc, 12, v209
	v_cmp_eq_u32_e64 s[14:15], 13, v209
	s_nop 0
	v_cndmask_b32_e64 v118, 0, 1.0, vcc
	v_cndmask_b32_e64 v119, 0, 1.0, s[14:15]
	v_cmp_eq_u32_e32 vcc, 14, v209
	v_cmp_eq_u32_e64 s[14:15], 15, v209
	s_nop 0
	v_cndmask_b32_e64 v120, 0, 1.0, vcc
	v_cndmask_b32_e64 v101, 0, 1.0, s[14:15]
	s_waitcnt lgkmcnt(6)
	v_fma_f32 v100, -v99, v140, v100
	v_fma_f32 v103, -v99, v144, v103
	v_fma_f32 v104, -v99, v148, v104
	v_fma_f32 v105, -v99, v152, v105
	v_fma_f32 v106, -v99, v156, v106
	v_fma_f32 v103, -v100, v145, v103
	v_fma_f32 v104, -v100, v149, v104
	v_fma_f32 v105, -v100, v153, v105
	v_fma_f32 v106, -v100, v157, v106
	v_fma_f32 v104, -v103, v150, v104
	v_fma_f32 v105, -v103, v154, v105
	v_fma_f32 v106, -v103, v158, v106
	v_fma_f32 v105, -v104, v155, v105
	v_fma_f32 v106, -v104, v159, v106
	v_fma_f32 v106, -v105, v160, v106
	ds_read_b128 v[140:143], v121 offset:2448
	ds_read_b128 v[144:147], v121 offset:2464
	ds_read_b128 v[148:151], v121 offset:2480
	ds_read_b128 v[152:155], v121 offset:2720
	ds_read_b128 v[156:159], v121 offset:2736
	ds_read_b128 v[160:163], v121 offset:2752
	ds_read_b128 v[232:235], v121 offset:2992
	ds_read_b128 v[236:239], v121 offset:3008
	ds_read_b128 v[240:243], v121 offset:3024
	s_waitcnt lgkmcnt(9)
	v_fma_f32 v107, -v99, v164, v107
	v_fma_f32 v108, -v99, v172, v108
	v_fma_f32 v109, -v99, v180, v109
	v_fma_f32 v107, -v100, v165, v107
	v_fma_f32 v108, -v100, v173, v108
	v_fma_f32 v109, -v100, v181, v109
	v_fma_f32 v107, -v103, v166, v107
	v_fma_f32 v108, -v103, v174, v108
	v_fma_f32 v109, -v103, v182, v109
	v_fma_f32 v107, -v104, v167, v107
	v_fma_f32 v108, -v104, v175, v108
	v_fma_f32 v109, -v104, v183, v109
	v_fma_f32 v107, -v105, v168, v107
	v_fma_f32 v108, -v105, v176, v108
	v_fma_f32 v109, -v105, v228, v109
	v_fma_f32 v107, -v106, v169, v107
	v_fma_f32 v108, -v106, v177, v108
	v_fma_f32 v109, -v106, v229, v109
	v_fma_f32 v108, -v107, v178, v108
	v_fma_f32 v109, -v107, v230, v109
	v_fma_f32 v109, -v108, v231, v109
	s_waitcnt lgkmcnt(0)
; #define LAS __attribute__((address_space(3)))
; __device__ __forceinline__ void rwkv_phase_a(const Ctx& C) {
;     ...
;             if (tid < 64) {
;                 const int blk = tid >> 4, col = tid & 15; const LAS float* L = FM(0) + (blk * 16) * MS + blk * 16;
;                 float x[16];
; #pragma unroll
;                 for (int r = 0; r < 16; ++r) {
;                     float a = (r == col) ? 1.f : 0.f;
; #pragma unroll
;                     for (int s2 = 0; s2 < r; ++s2) a -= L[r * MS + s2] * x[s2];
;                     x[r] = a;
;                 }
; #pragma unroll
;                 for (int r = 0; r < 16; ++r) DI[(blk * 16 + r) * 20 + col] = x[r];
;             }
	ds_read_b128 v[164:167], v121 offset:3264
	ds_read_b128 v[168:171], v121 offset:3280
	ds_read_b128 v[172:175], v121 offset:3296
	ds_read_b128 v[176:179], v121 offset:3536
	ds_read_b128 v[180:183], v121 offset:3552
	ds_read_b128 v[228:231], v121 offset:3568
	ds_read_b128 v[244:247], v121 offset:3584
	v_fma_f32 v111, -v99, v140, v111
	v_fma_f32 v112, -v99, v152, v112
	v_fma_f32 v113, -v99, v232, v113
	v_fma_f32 v111, -v100, v141, v111
	v_fma_f32 v112, -v100, v153, v112
	v_fma_f32 v113, -v100, v233, v113
	v_fma_f32 v111, -v103, v142, v111
	v_fma_f32 v112, -v103, v154, v112
	v_fma_f32 v113, -v103, v234, v113
	v_fma_f32 v111, -v104, v143, v111
	v_fma_f32 v112, -v104, v155, v112
	v_fma_f32 v113, -v104, v235, v113
	v_fma_f32 v111, -v105, v144, v111
	v_fma_f32 v112, -v105, v156, v112
	v_fma_f32 v113, -v105, v236, v113
	v_fma_f32 v111, -v106, v145, v111
	v_fma_f32 v112, -v106, v157, v112
	v_fma_f32 v113, -v106, v237, v113
	v_fma_f32 v111, -v107, v146, v111
	v_fma_f32 v112, -v107, v158, v112
	v_fma_f32 v113, -v107, v238, v113
	v_fma_f32 v111, -v108, v147, v111
	v_fma_f32 v112, -v108, v159, v112
	v_fma_f32 v113, -v108, v239, v113
	v_fma_f32 v111, -v109, v148, v111
	v_fma_f32 v112, -v109, v160, v112
	v_fma_f32 v113, -v109, v240, v113
	v_fma_f32 v112, -v111, v161, v112
	v_fma_f32 v113, -v111, v241, v113
	v_fma_f32 v113, -v112, v242, v113
	ds_read_b128 v[140:143], v121 offset:3808
	ds_read_b128 v[144:147], v121 offset:3824
	ds_read_b128 v[148:151], v121 offset:3840
	ds_read_b128 v[152:155], v121 offset:3856
	ds_read_b128 v[156:159], v121 offset:4080
	ds_read_b128 v[160:163], v121 offset:4096
	ds_read_b128 v[232:235], v121 offset:4112
	ds_read_b128 v[236:239], v121 offset:4128
	s_waitcnt lgkmcnt(8)
	v_fma_f32 v118, -v99, v164, v118
	v_fma_f32 v119, -v99, v176, v119
	v_fma_f32 v118, -v100, v165, v118
	v_fma_f32 v119, -v100, v177, v119
	v_fma_f32 v118, -v103, v166, v118
	v_fma_f32 v119, -v103, v178, v119
	v_fma_f32 v118, -v104, v167, v118
	v_fma_f32 v119, -v104, v179, v119
	v_fma_f32 v118, -v105, v168, v118
	v_fma_f32 v119, -v105, v180, v119
	v_fma_f32 v118, -v106, v169, v118
	v_fma_f32 v119, -v106, v181, v119
	v_fma_f32 v118, -v107, v170, v118
	v_fma_f32 v119, -v107, v182, v119
	v_fma_f32 v118, -v108, v171, v118
	v_fma_f32 v119, -v108, v183, v119
	v_fma_f32 v118, -v109, v172, v118
	v_fma_f32 v119, -v109, v228, v119
	v_fma_f32 v118, -v111, v173, v118
	v_fma_f32 v119, -v111, v229, v119
	v_fma_f32 v118, -v112, v174, v118
	v_fma_f32 v119, -v112, v230, v119
	v_fma_f32 v118, -v113, v175, v118
	v_fma_f32 v119, -v113, v231, v119
	v_fma_f32 v119, -v118, v244, v119
	s_waitcnt lgkmcnt(0)
	v_fma_f32 v120, -v99, v140, v120
	v_fma_f32 v101, -v99, v156, v101
	v_fma_f32 v120, -v100, v141, v120
	v_fma_f32 v101, -v100, v157, v101
	v_fma_f32 v120, -v103, v142, v120
	v_fma_f32 v101, -v103, v158, v101
	v_fma_f32 v120, -v104, v143, v120
	v_fma_f32 v101, -v104, v159, v101
	v_fma_f32 v120, -v105, v144, v120
	v_fma_f32 v101, -v105, v160, v101
	v_fma_f32 v120, -v106, v145, v120
	v_fma_f32 v101, -v106, v161, v101
	v_fma_f32 v120, -v107, v146, v120
	v_fma_f32 v101, -v107, v162, v101
	v_fma_f32 v120, -v108, v147, v120
	v_fma_f32 v101, -v108, v163, v101
	v_fma_f32 v120, -v109, v148, v120
	v_fma_f32 v101, -v109, v232, v101
	v_fma_f32 v120, -v111, v149, v120
	v_fma_f32 v101, -v111, v233, v101
	v_fma_f32 v120, -v112, v150, v120
	v_fma_f32 v101, -v112, v234, v101
	v_fma_f32 v120, -v113, v151, v120
	v_fma_f32 v101, -v113, v235, v101
	v_fma_f32 v120, -v118, v152, v120
	v_fma_f32 v101, -v118, v236, v101
	v_fma_f32 v120, -v119, v153, v120
	v_fma_f32 v101, -v119, v237, v101
	v_fma_f32 v101, -v120, v238, v101
	v_lshl_add_u32 v114, v209, 2, s69
	v_mad_u64_u32 v[116:117], s[14:15], v98, s21, v[114:115]
	v_add_u32_e32 v98, 0x200, v116
	ds_write2_b32 v116, v99, v100 offset1:20
	ds_write2_b32 v116, v103, v104 offset0:40 offset1:60
	ds_write2_b32 v116, v105, v106 offset0:80 offset1:100
	ds_write2_b32 v116, v107, v108 offset0:120 offset1:140
	ds_write2_b32 v116, v109, v111 offset0:160 offset1:180
	ds_write2_b32 v116, v112, v113 offset0:200 offset1:220
	ds_write2_b32 v98, v118, v119 offset0:112 offset1:132
	ds_write_b32 v116, v120 offset:1120
	v_or_b32_e32 v98, 15, v210
	v_mad_u64_u32 v[98:99], s[14:15], v98, s21, v[114:115]
	ds_write_b32 v98, v101

; __device__ __forceinline__ unsigned pk2(float lo, float hi) { const f32x2 v = {lo, hi}; const bf16x2_t b = __builtin_convertvector(v, bf16x2_t); return __builtin_bit_cast(unsigned, b); }
; __device__ __forceinline__ float frcp(float x) { return __builtin_amdgcn_rcpf(x); }
;     __device__ __forceinline__ void operator()(const f32x4 (&acc)[2][2][4][2], const Unit& u, int wr, int wc, int fr, int fq) const {
;         const int row0 = u.pm * 256 + wr * 64 + fr, col0 = u.pn * 128 + wc * 32 + 8 * fq;
; #pragma unroll
;         for (int ai = 0; ai < 2; ++ai)
; #pragma unroll
;             for (int m = 0; m < 4; ++m) {
;                 const int row = row0 + ai * 128 + m * 16; const float rs = row_rstd_q(ssq, row, fq);
;                 float h[8];
; #pragma unroll
;                 for (int n = 0; n < 2; ++n) {
;                     const f32x4 a = acc[ai][0][m][n] * rs, b = acc[ai][1][m][n] * rs;
; #pragma unroll
;                     for (int j = 0; j < 4; ++j) h[4 * n + j] = a[j] * frcp(1.0f + __expf(-a[j])) * b[j];
;                 }
;                 u32x4 w; w.x = pk2(h[0], h[1]); w.y = pk2(h[2], h[3]); w.z = pk2(h[4], h[5]); w.w = pk2(h[6], h[7]);
;                 *(u32x4*)(O + (size_t)row * FF_ + col0) = w;
;             }
.Lmy_p9_fast:
	v_lshl_add_u32 v152, s6, 8, v1
	v_mov_b64_e32 v[148:149], s[26:27]
	v_lshl_or_b32 v150, s7, 7, v155
	v_ashrrev_i32_e32 v151, 31, v150
	v_lshlrev_b64 v[150:151], 1, v[150:151]
	v_or_b32_e32 v166, 16, v152
	v_mad_i64_i32 v[164:165], s[6:7], v152, s60, v[148:149]
	v_lshl_add_u64 v[164:165], v[164:165], 0, v[150:151]
	v_mov_b32_e32 v170, v232
	v_pk_mul_f32 v[126:127], v[126:127], v[170:171] op_sel_hi:[1,0]
	v_pk_mul_f32 v[128:129], v[128:129], v[170:171] op_sel_hi:[1,0]
	v_pk_mul_f32 v[122:123], v[122:123], v[170:171] op_sel_hi:[1,0]
	v_pk_mul_f32 v[124:125], v[124:125], v[170:171] op_sel_hi:[1,0]
	v_pk_mul_f32 v[118:119], v[118:119], v[170:171] op_sel_hi:[1,0]
	v_pk_mul_f32 v[120:121], v[120:121], v[170:171] op_sel_hi:[1,0]
	v_pk_mul_f32 v[114:115], v[114:115], v[170:171] op_sel_hi:[1,0]
	v_pk_mul_f32 v[116:117], v[116:117], v[170:171] op_sel_hi:[1,0]
	v_mul_f32_e32 v163, 0xbfb8aa3b, v126
	v_mul_f32_e32 v167, 0xbfb8aa3b, v127
	v_mul_f32_e32 v170, 0xbfb8aa3b, v128
	v_mul_f32_e32 v171, 0xbfb8aa3b, v129
	v_mul_f32_e32 v172, 0xbfb8aa3b, v122
	v_mul_f32_e32 v173, 0xbfb8aa3b, v123
	v_mul_f32_e32 v174, 0xbfb8aa3b, v124
	v_mul_f32_e32 v175, 0xbfb8aa3b, v125
	v_exp_f32_e32 v163, v163
	v_exp_f32_e32 v167, v167
	v_exp_f32_e32 v170, v170
	v_exp_f32_e32 v171, v171
	v_exp_f32_e32 v172, v172
	v_exp_f32_e32 v173, v173
	v_exp_f32_e32 v174, v174
	v_exp_f32_e32 v175, v175
	v_add_f32_e32 v163, 1.0, v163
	v_add_f32_e32 v167, 1.0, v167
	v_add_f32_e32 v176, 1.0, v170
	v_add_f32_e32 v177, 1.0, v171
	v_add_f32_e32 v178, 1.0, v172
	v_add_f32_e32 v179, 1.0, v173
	v_add_f32_e32 v180, 1.0, v174
	v_add_f32_e32 v181, 1.0, v175
	v_rcp_f32_e32 v170, v163
	v_rcp_f32_e32 v171, v167
	v_rcp_f32_e32 v172, v176
	v_rcp_f32_e32 v173, v177
	v_rcp_f32_e32 v174, v178
	v_rcp_f32_e32 v175, v179
	v_rcp_f32_e32 v176, v180
	v_rcp_f32_e32 v177, v181
	v_pk_mul_f32 v[126:127], v[126:127], v[170:171]
	v_pk_mul_f32 v[128:129], v[128:129], v[172:173]
	v_pk_mul_f32 v[122:123], v[122:123], v[174:175]
	v_pk_mul_f32 v[124:125], v[124:125], v[176:177]
	v_pk_mul_f32 v[118:119], v[118:119], v[126:127]
	v_pk_mul_f32 v[120:121], v[120:121], v[128:129]
	v_pk_mul_f32 v[122:123], v[114:115], v[122:123]
	v_pk_mul_f32 v[124:125], v[116:117], v[124:125]
	v_cvt_pk_bf16_f32 v114, v118, v119
	v_cvt_pk_bf16_f32 v115, v120, v121
	v_cvt_pk_bf16_f32 v116, v122, v123
	v_cvt_pk_bf16_f32 v117, v124, v125
	global_store_dwordx4 v[164:165], v[114:117], off
	s_nop 1
	v_mad_i64_i32 v[116:117], s[6:7], v166, s60, v[148:149]
	v_lshl_add_u64 v[116:117], v[116:117], 0, v[150:151]
	v_or_b32_e32 v114, 32, v152
	v_mov_b32_e32 v120, v233
	v_pk_mul_f32 v[110:111], v[110:111], v[120:121] op_sel_hi:[1,0]
	v_pk_mul_f32 v[112:113], v[112:113], v[120:121] op_sel_hi:[1,0]
	v_pk_mul_f32 v[106:107], v[106:107], v[120:121] op_sel_hi:[1,0]
	v_pk_mul_f32 v[108:109], v[108:109], v[120:121] op_sel_hi:[1,0]
	v_pk_mul_f32 v[102:103], v[102:103], v[120:121] op_sel_hi:[1,0]
	v_pk_mul_f32 v[104:105], v[104:105], v[120:121] op_sel_hi:[1,0]
	v_pk_mul_f32 v[98:99], v[98:99], v[120:121] op_sel_hi:[1,0]
	v_pk_mul_f32 v[100:101], v[100:101], v[120:121] op_sel_hi:[1,0]
	v_mul_f32_e32 v115, 0xbfb8aa3b, v110
	v_mul_f32_e32 v120, 0xbfb8aa3b, v111
	v_mul_f32_e32 v121, 0xbfb8aa3b, v112
	v_mul_f32_e32 v122, 0xbfb8aa3b, v113
	v_mul_f32_e32 v123, 0xbfb8aa3b, v106
	v_mul_f32_e32 v124, 0xbfb8aa3b, v107
	v_mul_f32_e32 v125, 0xbfb8aa3b, v108
	v_mul_f32_e32 v126, 0xbfb8aa3b, v109
	v_exp_f32_e32 v115, v115
	v_exp_f32_e32 v120, v120
	v_exp_f32_e32 v121, v121
	v_exp_f32_e32 v122, v122
	v_exp_f32_e32 v123, v123
	v_exp_f32_e32 v124, v124
	v_exp_f32_e32 v125, v125
	v_exp_f32_e32 v126, v126
	v_add_f32_e32 v115, 1.0, v115
	v_add_f32_e32 v127, 1.0, v120
	v_add_f32_e32 v128, 1.0, v121
	v_add_f32_e32 v129, 1.0, v122
	v_add_f32_e32 v163, 1.0, v123
	v_add_f32_e32 v164, 1.0, v124
	v_add_f32_e32 v165, 1.0, v125
	v_add_f32_e32 v166, 1.0, v126
	v_rcp_f32_e32 v120, v115
	v_rcp_f32_e32 v121, v127
	v_rcp_f32_e32 v122, v128
	v_rcp_f32_e32 v123, v129
	v_rcp_f32_e32 v124, v163
	v_rcp_f32_e32 v125, v164
	v_rcp_f32_e32 v126, v165
	v_rcp_f32_e32 v127, v166
	v_pk_mul_f32 v[110:111], v[110:111], v[120:121]
	v_pk_mul_f32 v[112:113], v[112:113], v[122:123]
	v_pk_mul_f32 v[106:107], v[106:107], v[124:125]
	v_pk_mul_f32 v[108:109], v[108:109], v[126:127]
	v_pk_mul_f32 v[102:103], v[102:103], v[110:111]
	v_pk_mul_f32 v[104:105], v[104:105], v[112:113]
	v_pk_mul_f32 v[106:107], v[98:99], v[106:107]
	v_pk_mul_f32 v[108:109], v[100:101], v[108:109]
	v_cvt_pk_bf16_f32 v98, v102, v103
	v_cvt_pk_bf16_f32 v99, v104, v105
	v_cvt_pk_bf16_f32 v100, v106, v107
	v_cvt_pk_bf16_f32 v101, v108, v109
	global_store_dwordx4 v[116:117], v[98:101], off
	s_nop 1
	v_mad_i64_i32 v[100:101], s[6:7], v114, s60, v[148:149]
	v_lshl_add_u64 v[100:101], v[100:101], 0, v[150:151]
	v_or_b32_e32 v98, 48, v152
	v_mov_b32_e32 v104, v234
	v_pk_mul_f32 v[94:95], v[94:95], v[104:105] op_sel_hi:[1,0]
	v_pk_mul_f32 v[96:97], v[96:97], v[104:105] op_sel_hi:[1,0]
	v_pk_mul_f32 v[90:91], v[90:91], v[104:105] op_sel_hi:[1,0]
	v_pk_mul_f32 v[92:93], v[92:93], v[104:105] op_sel_hi:[1,0]
	v_pk_mul_f32 v[86:87], v[86:87], v[104:105] op_sel_hi:[1,0]
	v_pk_mul_f32 v[88:89], v[88:89], v[104:105] op_sel_hi:[1,0]
	v_pk_mul_f32 v[82:83], v[82:83], v[104:105] op_sel_hi:[1,0]
	v_pk_mul_f32 v[84:85], v[84:85], v[104:105] op_sel_hi:[1,0]
	v_mul_f32_e32 v99, 0xbfb8aa3b, v94
	v_mul_f32_e32 v104, 0xbfb8aa3b, v95
	v_mul_f32_e32 v105, 0xbfb8aa3b, v96
	v_mul_f32_e32 v106, 0xbfb8aa3b, v97
	v_mul_f32_e32 v107, 0xbfb8aa3b, v90
	v_mul_f32_e32 v108, 0xbfb8aa3b, v91
	v_mul_f32_e32 v109, 0xbfb8aa3b, v92
	v_mul_f32_e32 v110, 0xbfb8aa3b, v93
	v_exp_f32_e32 v99, v99
; __device__ __forceinline__ unsigned pk2(float lo, float hi) { const f32x2 v = {lo, hi}; const bf16x2_t b = __builtin_convertvector(v, bf16x2_t); return __builtin_bit_cast(unsigned, b); }
; __device__ __forceinline__ float frcp(float x) { return __builtin_amdgcn_rcpf(x); }
;     __device__ __forceinline__ void operator()(const f32x4 (&acc)[2][2][4][2], const Unit& u, int wr, int wc, int fr, int fq) const {
;         const int row0 = u.pm * 256 + wr * 64 + fr, col0 = u.pn * 128 + wc * 32 + 8 * fq;
; #pragma unroll
;         for (int ai = 0; ai < 2; ++ai)
; #pragma unroll
;             for (int m = 0; m < 4; ++m) {
;                 const int row = row0 + ai * 128 + m * 16; const float rs = row_rstd_q(ssq, row, fq);
;                 float h[8];
; #pragma unroll
;                 for (int n = 0; n < 2; ++n) {
;                     const f32x4 a = acc[ai][0][m][n] * rs, b = acc[ai][1][m][n] * rs;
; #pragma unroll
;                     for (int j = 0; j < 4; ++j) h[4 * n + j] = a[j] * frcp(1.0f + __expf(-a[j])) * b[j];
;                 }
;                 u32x4 w; w.x = pk2(h[0], h[1]); w.y = pk2(h[2], h[3]); w.z = pk2(h[4], h[5]); w.w = pk2(h[6], h[7]);
;                 *(u32x4*)(O + (size_t)row * FF_ + col0) = w;
;             }
	v_exp_f32_e32 v104, v104
	v_exp_f32_e32 v105, v105
	v_exp_f32_e32 v106, v106
	v_exp_f32_e32 v107, v107
	v_exp_f32_e32 v108, v108
	v_exp_f32_e32 v109, v109
	v_exp_f32_e32 v110, v110
	v_add_f32_e32 v99, 1.0, v99
	v_add_f32_e32 v111, 1.0, v104
	v_add_f32_e32 v112, 1.0, v105
	v_add_f32_e32 v113, 1.0, v106
	v_add_f32_e32 v114, 1.0, v107
	v_add_f32_e32 v115, 1.0, v108
	v_add_f32_e32 v116, 1.0, v109
	v_add_f32_e32 v117, 1.0, v110
	v_rcp_f32_e32 v104, v99
	v_rcp_f32_e32 v105, v111
	v_rcp_f32_e32 v106, v112
	v_rcp_f32_e32 v107, v113
	v_rcp_f32_e32 v108, v114
	v_rcp_f32_e32 v109, v115
	v_rcp_f32_e32 v110, v116
	v_rcp_f32_e32 v111, v117
	v_pk_mul_f32 v[94:95], v[94:95], v[104:105]
	v_pk_mul_f32 v[96:97], v[96:97], v[106:107]
	v_pk_mul_f32 v[90:91], v[90:91], v[108:109]
	v_pk_mul_f32 v[92:93], v[92:93], v[110:111]
	v_pk_mul_f32 v[86:87], v[86:87], v[94:95]
	v_pk_mul_f32 v[88:89], v[88:89], v[96:97]
	v_pk_mul_f32 v[90:91], v[82:83], v[90:91]
	v_pk_mul_f32 v[92:93], v[84:85], v[92:93]
	v_cvt_pk_bf16_f32 v82, v86, v87
	v_cvt_pk_bf16_f32 v83, v88, v89
	v_cvt_pk_bf16_f32 v84, v90, v91
	v_cvt_pk_bf16_f32 v85, v92, v93
	global_store_dwordx4 v[100:101], v[82:85], off
	s_nop 1
	v_mad_i64_i32 v[84:85], s[6:7], v98, s60, v[148:149]
	v_lshl_add_u64 v[84:85], v[84:85], 0, v[150:151]
	v_add_u32_e32 v82, 0x80, v152
	v_mov_b32_e32 v88, v235
	v_pk_mul_f32 v[78:79], v[78:79], v[88:89] op_sel_hi:[1,0]
	v_pk_mul_f32 v[80:81], v[80:81], v[88:89] op_sel_hi:[1,0]
	v_pk_mul_f32 v[74:75], v[74:75], v[88:89] op_sel_hi:[1,0]
	v_pk_mul_f32 v[76:77], v[76:77], v[88:89] op_sel_hi:[1,0]
	v_pk_mul_f32 v[70:71], v[70:71], v[88:89] op_sel_hi:[1,0]
	v_pk_mul_f32 v[72:73], v[72:73], v[88:89] op_sel_hi:[1,0]
	v_pk_mul_f32 v[66:67], v[66:67], v[88:89] op_sel_hi:[1,0]
	v_pk_mul_f32 v[68:69], v[68:69], v[88:89] op_sel_hi:[1,0]
	v_mul_f32_e32 v83, 0xbfb8aa3b, v78
	v_mul_f32_e32 v88, 0xbfb8aa3b, v79
	v_mul_f32_e32 v89, 0xbfb8aa3b, v80
	v_mul_f32_e32 v90, 0xbfb8aa3b, v81
	v_mul_f32_e32 v91, 0xbfb8aa3b, v74
	v_mul_f32_e32 v92, 0xbfb8aa3b, v75
	v_mul_f32_e32 v93, 0xbfb8aa3b, v76
	v_mul_f32_e32 v94, 0xbfb8aa3b, v77
	v_exp_f32_e32 v83, v83
	v_exp_f32_e32 v88, v88
	v_exp_f32_e32 v89, v89
	v_exp_f32_e32 v90, v90
	v_exp_f32_e32 v91, v91
	v_exp_f32_e32 v92, v92
	v_exp_f32_e32 v93, v93
	v_exp_f32_e32 v94, v94
	v_add_f32_e32 v83, 1.0, v83
	v_add_f32_e32 v95, 1.0, v88
	v_add_f32_e32 v96, 1.0, v89
	v_add_f32_e32 v97, 1.0, v90
	v_add_f32_e32 v98, 1.0, v91
	v_add_f32_e32 v99, 1.0, v92
	v_add_f32_e32 v100, 1.0, v93
	v_add_f32_e32 v101, 1.0, v94
	v_rcp_f32_e32 v88, v83
	v_rcp_f32_e32 v89, v95
	v_rcp_f32_e32 v90, v96
	v_rcp_f32_e32 v91, v97
	v_rcp_f32_e32 v92, v98
	v_rcp_f32_e32 v93, v99
	v_rcp_f32_e32 v94, v100
	v_rcp_f32_e32 v95, v101
	v_pk_mul_f32 v[78:79], v[78:79], v[88:89]
	v_pk_mul_f32 v[80:81], v[80:81], v[90:91]
	v_pk_mul_f32 v[74:75], v[74:75], v[92:93]
	v_pk_mul_f32 v[76:77], v[76:77], v[94:95]
	v_pk_mul_f32 v[70:71], v[70:71], v[78:79]
	v_pk_mul_f32 v[72:73], v[72:73], v[80:81]
	v_pk_mul_f32 v[74:75], v[66:67], v[74:75]
	v_pk_mul_f32 v[76:77], v[68:69], v[76:77]
	v_cvt_pk_bf16_f32 v66, v70, v71
	v_cvt_pk_bf16_f32 v67, v72, v73
	v_cvt_pk_bf16_f32 v68, v74, v75
	v_cvt_pk_bf16_f32 v69, v76, v77
	global_store_dwordx4 v[84:85], v[66:69], off
	s_nop 1
	v_mad_i64_i32 v[68:69], s[6:7], v82, s60, v[148:149]
	v_lshl_add_u64 v[68:69], v[68:69], 0, v[150:151]
	v_add_u32_e32 v66, 0x90, v152
	v_mov_b32_e32 v72, v236
	v_pk_mul_f32 v[62:63], v[62:63], v[72:73] op_sel_hi:[1,0]
	v_pk_mul_f32 v[64:65], v[64:65], v[72:73] op_sel_hi:[1,0]
	v_pk_mul_f32 v[58:59], v[58:59], v[72:73] op_sel_hi:[1,0]
	v_pk_mul_f32 v[60:61], v[60:61], v[72:73] op_sel_hi:[1,0]
	v_pk_mul_f32 v[54:55], v[54:55], v[72:73] op_sel_hi:[1,0]
	v_pk_mul_f32 v[56:57], v[56:57], v[72:73] op_sel_hi:[1,0]
	v_pk_mul_f32 v[50:51], v[50:51], v[72:73] op_sel_hi:[1,0]
	v_pk_mul_f32 v[52:53], v[52:53], v[72:73] op_sel_hi:[1,0]
	v_mul_f32_e32 v67, 0xbfb8aa3b, v62
	v_mul_f32_e32 v72, 0xbfb8aa3b, v63
	v_mul_f32_e32 v73, 0xbfb8aa3b, v64
	v_mul_f32_e32 v74, 0xbfb8aa3b, v65
	v_mul_f32_e32 v75, 0xbfb8aa3b, v58
	v_mul_f32_e32 v76, 0xbfb8aa3b, v59
	v_mul_f32_e32 v77, 0xbfb8aa3b, v60
	v_mul_f32_e32 v78, 0xbfb8aa3b, v61
	v_exp_f32_e32 v67, v67
	v_exp_f32_e32 v72, v72
	v_exp_f32_e32 v73, v73
	v_exp_f32_e32 v74, v74
	v_exp_f32_e32 v75, v75
	v_exp_f32_e32 v76, v76
	v_exp_f32_e32 v77, v77
	v_exp_f32_e32 v78, v78
	v_add_f32_e32 v67, 1.0, v67
	v_add_f32_e32 v79, 1.0, v72
	v_add_f32_e32 v80, 1.0, v73
	v_add_f32_e32 v81, 1.0, v74
	v_add_f32_e32 v82, 1.0, v75
	v_add_f32_e32 v83, 1.0, v76
	v_add_f32_e32 v84, 1.0, v77
	v_add_f32_e32 v85, 1.0, v78
	v_rcp_f32_e32 v72, v67
	v_rcp_f32_e32 v73, v79
	v_rcp_f32_e32 v74, v80
	v_rcp_f32_e32 v75, v81
	v_rcp_f32_e32 v76, v82
	v_rcp_f32_e32 v77, v83
	v_rcp_f32_e32 v78, v84
	v_rcp_f32_e32 v79, v85
	v_pk_mul_f32 v[62:63], v[62:63], v[72:73]
	v_pk_mul_f32 v[64:65], v[64:65], v[74:75]
	v_pk_mul_f32 v[58:59], v[58:59], v[76:77]
	v_pk_mul_f32 v[60:61], v[60:61], v[78:79]
	v_pk_mul_f32 v[54:55], v[54:55], v[62:63]
	v_pk_mul_f32 v[56:57], v[56:57], v[64:65]
	v_pk_mul_f32 v[58:59], v[50:51], v[58:59]
	v_pk_mul_f32 v[60:61], v[52:53], v[60:61]
	v_cvt_pk_bf16_f32 v50, v54, v55
	v_cvt_pk_bf16_f32 v51, v56, v57
	v_cvt_pk_bf16_f32 v52, v58, v59
	v_cvt_pk_bf16_f32 v53, v60, v61
	global_store_dwordx4 v[68:69], v[50:53], off
	s_nop 1
	v_mad_i64_i32 v[52:53], s[6:7], v66, s60, v[148:149]
	v_lshl_add_u64 v[52:53], v[52:53], 0, v[150:151]
	v_add_u32_e32 v50, 0xa0, v152
	v_mov_b32_e32 v56, v237
	v_pk_mul_f32 v[46:47], v[46:47], v[56:57] op_sel_hi:[1,0]
	v_pk_mul_f32 v[48:49], v[48:49], v[56:57] op_sel_hi:[1,0]
	v_pk_mul_f32 v[42:43], v[42:43], v[56:57] op_sel_hi:[1,0]
; __device__ __forceinline__ unsigned pk2(float lo, float hi) { const f32x2 v = {lo, hi}; const bf16x2_t b = __builtin_convertvector(v, bf16x2_t); return __builtin_bit_cast(unsigned, b); }
; __device__ __forceinline__ float frcp(float x) { return __builtin_amdgcn_rcpf(x); }
;     __device__ __forceinline__ void operator()(const f32x4 (&acc)[2][2][4][2], const Unit& u, int wr, int wc, int fr, int fq) const {
;         const int row0 = u.pm * 256 + wr * 64 + fr, col0 = u.pn * 128 + wc * 32 + 8 * fq;
; #pragma unroll
;         for (int ai = 0; ai < 2; ++ai)
; #pragma unroll
;             for (int m = 0; m < 4; ++m) {
;                 const int row = row0 + ai * 128 + m * 16; const float rs = row_rstd_q(ssq, row, fq);
;                 float h[8];
; #pragma unroll
;                 for (int n = 0; n < 2; ++n) {
;                     const f32x4 a = acc[ai][0][m][n] * rs, b = acc[ai][1][m][n] * rs;
; #pragma unroll
;                     for (int j = 0; j < 4; ++j) h[4 * n + j] = a[j] * frcp(1.0f + __expf(-a[j])) * b[j];
;                 }
;                 u32x4 w; w.x = pk2(h[0], h[1]); w.y = pk2(h[2], h[3]); w.z = pk2(h[4], h[5]); w.w = pk2(h[6], h[7]);
;                 *(u32x4*)(O + (size_t)row * FF_ + col0) = w;
;             }
	v_pk_mul_f32 v[44:45], v[44:45], v[56:57] op_sel_hi:[1,0]
	v_pk_mul_f32 v[38:39], v[38:39], v[56:57] op_sel_hi:[1,0]
	v_pk_mul_f32 v[40:41], v[40:41], v[56:57] op_sel_hi:[1,0]
	v_pk_mul_f32 v[34:35], v[34:35], v[56:57] op_sel_hi:[1,0]
	v_pk_mul_f32 v[36:37], v[36:37], v[56:57] op_sel_hi:[1,0]
	v_mul_f32_e32 v51, 0xbfb8aa3b, v46
	v_mul_f32_e32 v56, 0xbfb8aa3b, v47
	v_mul_f32_e32 v57, 0xbfb8aa3b, v48
	v_mul_f32_e32 v58, 0xbfb8aa3b, v49
	v_mul_f32_e32 v59, 0xbfb8aa3b, v42
	v_mul_f32_e32 v60, 0xbfb8aa3b, v43
	v_mul_f32_e32 v61, 0xbfb8aa3b, v44
	v_mul_f32_e32 v62, 0xbfb8aa3b, v45
	v_exp_f32_e32 v51, v51
	v_exp_f32_e32 v56, v56
	v_exp_f32_e32 v57, v57
	v_exp_f32_e32 v58, v58
	v_exp_f32_e32 v59, v59
	v_exp_f32_e32 v60, v60
	v_exp_f32_e32 v61, v61
	v_exp_f32_e32 v62, v62
	v_add_f32_e32 v51, 1.0, v51
	v_add_f32_e32 v63, 1.0, v56
	v_add_f32_e32 v64, 1.0, v57
	v_add_f32_e32 v65, 1.0, v58
	v_add_f32_e32 v66, 1.0, v59
	v_add_f32_e32 v67, 1.0, v60
	v_add_f32_e32 v68, 1.0, v61
	v_add_f32_e32 v69, 1.0, v62
	v_rcp_f32_e32 v56, v51
	v_rcp_f32_e32 v57, v63
	v_rcp_f32_e32 v58, v64
	v_rcp_f32_e32 v59, v65
	v_rcp_f32_e32 v60, v66
	v_rcp_f32_e32 v61, v67
	v_rcp_f32_e32 v62, v68
	v_rcp_f32_e32 v63, v69
	v_pk_mul_f32 v[46:47], v[46:47], v[56:57]
	v_pk_mul_f32 v[48:49], v[48:49], v[58:59]
	v_pk_mul_f32 v[42:43], v[42:43], v[60:61]
	v_pk_mul_f32 v[44:45], v[44:45], v[62:63]
	v_pk_mul_f32 v[38:39], v[38:39], v[46:47]
	v_pk_mul_f32 v[40:41], v[40:41], v[48:49]
	v_pk_mul_f32 v[42:43], v[34:35], v[42:43]
	v_pk_mul_f32 v[44:45], v[36:37], v[44:45]
	v_cvt_pk_bf16_f32 v34, v38, v39
	v_cvt_pk_bf16_f32 v35, v40, v41
	v_cvt_pk_bf16_f32 v36, v42, v43
	v_cvt_pk_bf16_f32 v37, v44, v45
	global_store_dwordx4 v[52:53], v[34:37], off
	s_nop 1
	v_mad_i64_i32 v[36:37], s[6:7], v50, s60, v[148:149]
	v_lshl_add_u64 v[36:37], v[36:37], 0, v[150:151]
	v_add_u32_e32 v34, 0xb0, v152
	v_mov_b32_e32 v40, v238
	v_pk_mul_f32 v[30:31], v[30:31], v[40:41] op_sel_hi:[1,0]
	v_pk_mul_f32 v[32:33], v[32:33], v[40:41] op_sel_hi:[1,0]
	v_pk_mul_f32 v[26:27], v[26:27], v[40:41] op_sel_hi:[1,0]
	v_pk_mul_f32 v[28:29], v[28:29], v[40:41] op_sel_hi:[1,0]
	v_pk_mul_f32 v[22:23], v[22:23], v[40:41] op_sel_hi:[1,0]
	v_pk_mul_f32 v[24:25], v[24:25], v[40:41] op_sel_hi:[1,0]
	v_pk_mul_f32 v[18:19], v[18:19], v[40:41] op_sel_hi:[1,0]
	v_pk_mul_f32 v[20:21], v[20:21], v[40:41] op_sel_hi:[1,0]
	v_mul_f32_e32 v35, 0xbfb8aa3b, v30
	v_mul_f32_e32 v40, 0xbfb8aa3b, v31
	v_mul_f32_e32 v41, 0xbfb8aa3b, v32
	v_mul_f32_e32 v42, 0xbfb8aa3b, v33
	v_mul_f32_e32 v43, 0xbfb8aa3b, v26
	v_mul_f32_e32 v44, 0xbfb8aa3b, v27
	v_mul_f32_e32 v45, 0xbfb8aa3b, v28
	v_mul_f32_e32 v46, 0xbfb8aa3b, v29
	v_exp_f32_e32 v35, v35
	v_exp_f32_e32 v40, v40
	v_exp_f32_e32 v41, v41
	v_exp_f32_e32 v42, v42
	v_exp_f32_e32 v43, v43
	v_exp_f32_e32 v44, v44
	v_exp_f32_e32 v45, v45
	v_exp_f32_e32 v46, v46
	v_add_f32_e32 v35, 1.0, v35
	v_add_f32_e32 v47, 1.0, v40
	v_add_f32_e32 v48, 1.0, v41
	v_add_f32_e32 v49, 1.0, v42
	v_add_f32_e32 v50, 1.0, v43
	v_add_f32_e32 v51, 1.0, v44
	v_add_f32_e32 v52, 1.0, v45
	v_add_f32_e32 v53, 1.0, v46
	v_rcp_f32_e32 v40, v35
	v_rcp_f32_e32 v41, v47
	v_rcp_f32_e32 v42, v48
	v_rcp_f32_e32 v43, v49
	v_rcp_f32_e32 v44, v50
	v_rcp_f32_e32 v45, v51
	v_rcp_f32_e32 v46, v52
	v_rcp_f32_e32 v47, v53
	v_pk_mul_f32 v[30:31], v[30:31], v[40:41]
	v_pk_mul_f32 v[32:33], v[32:33], v[42:43]
	v_pk_mul_f32 v[26:27], v[26:27], v[44:45]
	v_pk_mul_f32 v[28:29], v[28:29], v[46:47]
	v_pk_mul_f32 v[22:23], v[22:23], v[30:31]
	v_pk_mul_f32 v[24:25], v[24:25], v[32:33]
	v_pk_mul_f32 v[26:27], v[18:19], v[26:27]
	v_pk_mul_f32 v[28:29], v[20:21], v[28:29]
	v_cvt_pk_bf16_f32 v18, v22, v23
	v_cvt_pk_bf16_f32 v19, v24, v25
	v_cvt_pk_bf16_f32 v20, v26, v27
	v_cvt_pk_bf16_f32 v21, v28, v29
	global_store_dwordx4 v[36:37], v[18:21], off
	s_nop 1
	v_mad_i64_i32 v[18:19], s[6:7], v34, s60, v[148:149]
	v_lshl_add_u64 v[18:19], v[18:19], 0, v[150:151]
	v_mov_b32_e32 v20, v239
	v_pk_mul_f32 v[14:15], v[14:15], v[20:21] op_sel_hi:[1,0]
	v_pk_mul_f32 v[16:17], v[16:17], v[20:21] op_sel_hi:[1,0]
	v_pk_mul_f32 v[10:11], v[10:11], v[20:21] op_sel_hi:[1,0]
	v_pk_mul_f32 v[12:13], v[12:13], v[20:21] op_sel_hi:[1,0]
	v_pk_mul_f32 v[6:7], v[6:7], v[20:21] op_sel_hi:[1,0]
	v_pk_mul_f32 v[8:9], v[8:9], v[20:21] op_sel_hi:[1,0]
	v_pk_mul_f32 v[2:3], v[2:3], v[20:21] op_sel_hi:[1,0]
	v_pk_mul_f32 v[4:5], v[4:5], v[20:21] op_sel_hi:[1,0]
	v_mul_f32_e32 v20, 0xbfb8aa3b, v14
	v_mul_f32_e32 v21, 0xbfb8aa3b, v15
	v_mul_f32_e32 v22, 0xbfb8aa3b, v16
	v_mul_f32_e32 v23, 0xbfb8aa3b, v17
	v_mul_f32_e32 v24, 0xbfb8aa3b, v10
	v_mul_f32_e32 v25, 0xbfb8aa3b, v11
	v_mul_f32_e32 v26, 0xbfb8aa3b, v12
	v_mul_f32_e32 v27, 0xbfb8aa3b, v13
	v_exp_f32_e32 v20, v20
	v_exp_f32_e32 v21, v21
	v_exp_f32_e32 v22, v22
	v_exp_f32_e32 v23, v23
	v_exp_f32_e32 v24, v24
	v_exp_f32_e32 v25, v25
	v_exp_f32_e32 v26, v26
	v_exp_f32_e32 v27, v27
	v_add_f32_e32 v20, 1.0, v20
	v_add_f32_e32 v21, 1.0, v21
	v_add_f32_e32 v22, 1.0, v22
	v_add_f32_e32 v23, 1.0, v23
	v_add_f32_e32 v24, 1.0, v24
	v_add_f32_e32 v25, 1.0, v25
	v_add_f32_e32 v26, 1.0, v26
	v_add_f32_e32 v27, 1.0, v27
	v_rcp_f32_e32 v20, v20
	v_rcp_f32_e32 v21, v21
	v_rcp_f32_e32 v22, v22
	v_rcp_f32_e32 v23, v23
	v_rcp_f32_e32 v24, v24
	v_rcp_f32_e32 v25, v25
	v_rcp_f32_e32 v26, v26
	v_rcp_f32_e32 v27, v27
	v_pk_mul_f32 v[14:15], v[14:15], v[20:21]
	v_pk_mul_f32 v[16:17], v[16:17], v[22:23]
	v_pk_mul_f32 v[10:11], v[10:11], v[24:25]
	v_pk_mul_f32 v[12:13], v[12:13], v[26:27]
	v_pk_mul_f32 v[6:7], v[6:7], v[14:15]
	v_pk_mul_f32 v[8:9], v[8:9], v[16:17]
	v_pk_mul_f32 v[10:11], v[2:3], v[10:11]
	v_pk_mul_f32 v[12:13], v[4:5], v[12:13]
	s_andn2_b64 vcc, exec, s[0:1]
	v_cvt_pk_bf16_f32 v2, v6, v7
	v_cvt_pk_bf16_f32 v3, v8, v9
	v_cvt_pk_bf16_f32 v4, v10, v11
	v_cvt_pk_bf16_f32 v5, v12, v13
	s_mov_b64 s[0:1], -1
	global_store_dwordx4 v[18:19], v[2:5], off
	s_nop 1
